# EpiResid epilogues (out-proj, down): residual loads of all 8 row groups hoisted to epilogue top, counted vmcnt instead of per-group vmcnt(0)
# speedup vs baseline: 1.0067x; 1.0067x over previous
; __device__ __forceinline__ float bf_lo(unsigned u) { return __uint_as_float(u << 16); }
; __device__ __forceinline__ float bf_hi(unsigned u) { return __uint_as_float(u & 0xffff0000u); }
; __device__ __forceinline__ unsigned pk_bf16(float lo, float hi) { const f32x2 v = {lo, hi}; const bf16x2_t b = __builtin_convertvector(v, bf16x2_t); return __builtin_bit_cast(unsigned, b); }
;     __device__ __forceinline__ void operator()(const f32x4 (&acc)[2][2][4][2], const pg8::Unit& u, int wr, int wc, int fr, int fq) const {
;         asm volatile("" : "+v"(fr));
;         const int row0 = u.pm * 256 + wr * 64 + fr, col0 = u.pn * 256 + wc * 32 + 4 * fq;
;         const bool rf32 = (rp != nullptr) && (u.pm < MP / 256);
; #pragma unroll
;         for (int ai = 0; ai < 2; ++ai)
; #pragma unroll
;             for (int m = 0; m < 4; ++m) {
;                 const int row = row0 + ai * 128 + m * 16; const size_t off = (size_t)row * DM + col0; float q = 0.f;
;                 f32x4 r4[2][2];
;                 if (rf32) {
; #pragma unroll
;                     for (int bj = 0; bj < 2; ++bj)
; #pragma unroll
;                         for (int n = 0; n < 2; ++n) r4[bj][n] = *(const f32x4*)(rp + off + bj * 128 + n * 16);
;                 } else {
; #pragma unroll
;                     for (int bj = 0; bj < 2; ++bj)
; #pragma unroll
;                         for (int n = 0; n < 2; ++n) { const u32x2 w = *(const u32x2*)(XB + off + bj * 128 + n * 16); r4[bj][n] = (f32x4){bf_lo(w.x), bf_hi(w.x), bf_lo(w.y), bf_hi(w.y)}; }
;                 }
; #pragma unroll
;                 for (int bj = 0; bj < 2; ++bj)
; #pragma unroll
;                     for (int n = 0; n < 2; ++n) { const f32x4 x4 = r4[bj][n] + acc[ai][bj][m][n];
;                         q += (x4[0] * x4[0] + x4[1] * x4[1]) + (x4[2] * x4[2] + x4[3] * x4[3]);
;                         u32x2 w; w.x = pk_bf16(x4[0], x4[1]); w.y = pk_bf16(x4[2], x4[3]); *(u32x2*)(XB + off + bj * 128 + n * 16) = w; }
;                 q += __shfl_xor(q, 16); q += __shfl_xor(q, 32);
;                 if (fq == 0) ssq[(size_t)row * 16 + u.pn * 4 + wc] = q;
.LBB0_1683:
	s_lshl_b32 s4, s51, 8
	v_mov_b32_e32 v158, v1
	s_add_i32 s4, s4, s46
	s_lshl_b32 s28, s50, 2
	v_add_u32_e32 v160, s4, v158
	v_ashrrev_i32_e32 v161, 31, v160
	v_lshl_or_b32 v158, s50, 8, v163
	v_lshlrev_b64 v[166:167], 11, v[160:161]
	v_ashrrev_i32_e32 v159, 31, v158
	v_lshl_add_u64 v[166:167], s[14:15], 0, v[166:167]
	v_lshl_add_u64 v[166:167], v[158:159], 1, v[166:167]
	v_lshlrev_b32_e32 v252, 11, v160
	v_lshl_add_u32 v252, v158, 1, v252
	global_load_dwordx2 v[184:185], v252, s[14:15]
	global_load_dwordx2 v[186:187], v252, s[14:15] offset:32
	global_load_dwordx2 v[188:189], v252, s[14:15] offset:256
	global_load_dwordx2 v[202:203], v252, s[14:15] offset:288
	v_add_u32_e32 v253, 0x8000, v252
	global_load_dwordx2 v[204:205], v253, s[14:15]
	global_load_dwordx2 v[206:207], v253, s[14:15] offset:32
	global_load_dwordx2 v[208:209], v253, s[14:15] offset:256
	global_load_dwordx2 v[210:211], v253, s[14:15] offset:288
	v_add_u32_e32 v253, 0x10000, v252
	global_load_dwordx2 v[212:213], v253, s[14:15]
	global_load_dwordx2 v[214:215], v253, s[14:15] offset:32
	global_load_dwordx2 v[216:217], v253, s[14:15] offset:256
	global_load_dwordx2 v[218:219], v253, s[14:15] offset:288
	v_add_u32_e32 v253, 0x18000, v252
	global_load_dwordx2 v[220:221], v253, s[14:15]
	global_load_dwordx2 v[222:223], v253, s[14:15] offset:32
	global_load_dwordx2 v[224:225], v253, s[14:15] offset:256
	global_load_dwordx2 v[226:227], v253, s[14:15] offset:288
	v_add_u32_e32 v253, 0x40000, v252
	global_load_dwordx2 v[228:229], v253, s[14:15]
	global_load_dwordx2 v[230:231], v253, s[14:15] offset:32
	global_load_dwordx2 v[232:233], v253, s[14:15] offset:256
	global_load_dwordx2 v[234:235], v253, s[14:15] offset:288
	v_add_u32_e32 v253, 0x48000, v252
	global_load_dwordx2 v[236:237], v253, s[14:15]
	global_load_dwordx2 v[238:239], v253, s[14:15] offset:32
	global_load_dwordx2 v[240:241], v253, s[14:15] offset:256
	global_load_dwordx2 v[242:243], v253, s[14:15] offset:288
	v_add_u32_e32 v253, 0x50000, v252
	global_load_dwordx2 v[244:245], v253, s[14:15]
	global_load_dwordx2 v[246:247], v253, s[14:15] offset:32
	global_load_dwordx2 v[248:249], v253, s[14:15] offset:256
	global_load_dwordx2 v[250:251], v253, s[14:15] offset:288
	s_ashr_i32 s29, s28, 31
	s_waitcnt vmcnt(24)
	v_lshlrev_b32_e32 v176, 16, v184
	v_and_b32_e32 v177, 0xffff0000, v184
	v_lshlrev_b32_e32 v168, 16, v185
	v_and_b32_e32 v169, 0xffff0000, v185
	v_lshlrev_b32_e32 v178, 16, v186
	v_and_b32_e32 v179, 0xffff0000, v186
	v_lshlrev_b32_e32 v170, 16, v187
	v_and_b32_e32 v171, 0xffff0000, v187
	v_lshlrev_b32_e32 v180, 16, v188
	v_and_b32_e32 v181, 0xffff0000, v188
	v_lshlrev_b32_e32 v172, 16, v189
	v_and_b32_e32 v173, 0xffff0000, v189
	v_lshlrev_b32_e32 v182, 16, v202
	v_and_b32_e32 v183, 0xffff0000, v202
	v_pk_add_f32 v[128:129], v[128:129], v[168:169]
	v_pk_add_f32 v[126:127], v[126:127], v[176:177]
	v_pk_add_f32 v[124:125], v[124:125], v[170:171]
	v_pk_add_f32 v[122:123], v[122:123], v[178:179]
	v_lshlrev_b32_e32 v174, 16, v203
	v_and_b32_e32 v175, 0xffff0000, v203
	v_add_u32_e32 v253, 0x58000, v252
	global_load_dwordx2 v[184:185], v253, s[14:15]
	global_load_dwordx2 v[186:187], v253, s[14:15] offset:32
	global_load_dwordx2 v[188:189], v253, s[14:15] offset:256
	global_load_dwordx2 v[202:203], v253, s[14:15] offset:288
	v_pk_add_f32 v[120:121], v[120:121], v[172:173]
	v_pk_add_f32 v[118:119], v[118:119], v[180:181]
	v_pk_add_f32 v[168:169], v[114:115], v[182:183]
	v_mul_f32_e32 v165, v127, v127
	v_mul_f32_e32 v171, v129, v129
	v_cvt_pk_bf16_f32 v114, v126, v127
	v_cvt_pk_bf16_f32 v115, v128, v129
	v_mul_f32_e32 v127, v123, v123
	v_mul_f32_e32 v129, v125, v125
	v_pk_add_f32 v[116:117], v[116:117], v[174:175]
	v_cvt_pk_bf16_f32 v170, v122, v123
	v_mul_f32_e32 v123, v119, v119
	v_mul_f32_e32 v172, v121, v121
	v_fmac_f32_e32 v165, v126, v126
	v_fmac_f32_e32 v171, v128, v128
	v_fmac_f32_e32 v127, v122, v122
	v_fmac_f32_e32 v129, v124, v124
	v_mul_f32_e32 v173, v169, v169
	v_mul_f32_e32 v174, v117, v117
	global_store_dwordx2 v[166:167], v[114:115], off
	v_fmac_f32_e32 v123, v118, v118
	v_fmac_f32_e32 v172, v120, v120
	v_add_f32_e32 v114, v165, v171
	v_add_f32_e32 v115, v127, v129
	v_fmac_f32_e32 v173, v168, v168
	v_fmac_f32_e32 v174, v116, v116
	v_add_f32_e32 v122, v123, v172
	v_add_f32_e32 v114, v114, v115
	v_add_f32_e32 v114, v114, v122
	v_add_f32_e32 v115, v173, v174
	v_add_f32_e32 v114, v114, v115
	ds_bpermute_b32 v115, v131, v114
	v_cvt_pk_bf16_f32 v118, v118, v119
	v_cvt_pk_bf16_f32 v119, v120, v121
	v_cvt_pk_bf16_f32 v171, v124, v125
	global_store_dwordx2 v[166:167], v[118:119], off offset:256
	s_waitcnt lgkmcnt(0)
	v_add_f32_e32 v114, v114, v115
	ds_bpermute_b32 v115, v135, v114
	v_cvt_pk_bf16_f32 v118, v168, v169
	v_cvt_pk_bf16_f32 v119, v116, v117
	global_store_dwordx2 v[166:167], v[170:171], off offset:32
	global_store_dwordx2 v[166:167], v[118:119], off offset:288
	s_and_saveexec_b64 s[30:31], s[8:9]
	s_cbranch_execz .LBB0_1685
	v_lshlrev_b64 v[116:117], 6, v[160:161]
	v_lshl_add_u64 v[116:117], s[16:17], 0, v[116:117]
	v_lshl_add_u64 v[116:117], s[28:29], 2, v[116:117]
	s_lshl_b32 s88, s45, 2
	v_lshl_add_u64 v[116:117], v[116:117], 0, s[88:89]
	s_waitcnt lgkmcnt(0)
	v_add_f32_e32 v114, v114, v115
	global_store_dword v[116:117], v114, off
; __device__ __forceinline__ float bf_lo(unsigned u) { return __uint_as_float(u << 16); }
; __device__ __forceinline__ float bf_hi(unsigned u) { return __uint_as_float(u & 0xffff0000u); }
; __device__ __forceinline__ unsigned pk_bf16(float lo, float hi) { const f32x2 v = {lo, hi}; const bf16x2_t b = __builtin_convertvector(v, bf16x2_t); return __builtin_bit_cast(unsigned, b); }
;     __device__ __forceinline__ void operator()(const f32x4 (&acc)[2][2][4][2], const pg8::Unit& u, int wr, int wc, int fr, int fq) const {
;     ...
;         for (int ai = 0; ai < 2; ++ai)
; #pragma unroll
;             for (int m = 0; m < 4; ++m) {
;                 const int row = row0 + ai * 128 + m * 16; const size_t off = (size_t)row * DM + col0; float q = 0.f;
;                 f32x4 r4[2][2];
;                 if (rf32) {
; #pragma unroll
;                     for (int bj = 0; bj < 2; ++bj)
; #pragma unroll
;                         for (int n = 0; n < 2; ++n) r4[bj][n] = *(const f32x4*)(rp + off + bj * 128 + n * 16);
;                 } else {
; #pragma unroll
;                     for (int bj = 0; bj < 2; ++bj)
; #pragma unroll
;                         for (int n = 0; n < 2; ++n) { const u32x2 w = *(const u32x2*)(XB + off + bj * 128 + n * 16); r4[bj][n] = (f32x4){bf_lo(w.x), bf_hi(w.x), bf_lo(w.y), bf_hi(w.y)}; }
;                 }
; #pragma unroll
;                 for (int bj = 0; bj < 2; ++bj)
; #pragma unroll
;                     for (int n = 0; n < 2; ++n) { const f32x4 x4 = r4[bj][n] + acc[ai][bj][m][n];
;                         q += (x4[0] * x4[0] + x4[1] * x4[1]) + (x4[2] * x4[2] + x4[3] * x4[3]);
;                         u32x2 w; w.x = pk_bf16(x4[0], x4[1]); w.y = pk_bf16(x4[2], x4[3]); *(u32x2*)(XB + off + bj * 128 + n * 16) = w; }
;                 q += __shfl_xor(q, 16); q += __shfl_xor(q, 32);
;                 if (fq == 0) ssq[(size_t)row * 16 + u.pn * 4 + wc] = q;
.LBB0_1685:
	s_or_b64 exec, exec, s[30:31]
	v_add_u32_e32 v114, 16, v160
	s_waitcnt lgkmcnt(0)
	v_ashrrev_i32_e32 v115, 31, v114
	v_lshlrev_b64 v[116:117], 11, v[114:115]
	v_lshl_add_u64 v[116:117], s[14:15], 0, v[116:117]
	v_lshl_add_u64 v[116:117], v[158:159], 1, v[116:117]
	s_waitcnt vmcnt(28)
	v_lshlrev_b32_e32 v126, 16, v204
	v_and_b32_e32 v127, 0xffff0000, v204
	v_lshlrev_b32_e32 v118, 16, v205
	v_and_b32_e32 v119, 0xffff0000, v205
	v_lshlrev_b32_e32 v128, 16, v206
	v_and_b32_e32 v129, 0xffff0000, v206
	v_lshlrev_b32_e32 v120, 16, v207
	v_and_b32_e32 v121, 0xffff0000, v207
	v_lshlrev_b32_e32 v166, 16, v208
	v_and_b32_e32 v167, 0xffff0000, v208
	v_lshlrev_b32_e32 v122, 16, v209
	v_and_b32_e32 v123, 0xffff0000, v209
	v_lshlrev_b32_e32 v168, 16, v210
	v_and_b32_e32 v169, 0xffff0000, v210
	v_pk_add_f32 v[112:113], v[112:113], v[118:119]
	v_pk_add_f32 v[110:111], v[110:111], v[126:127]
	v_pk_add_f32 v[108:109], v[108:109], v[120:121]
	v_pk_add_f32 v[106:107], v[106:107], v[128:129]
	v_lshlrev_b32_e32 v124, 16, v211
	v_and_b32_e32 v125, 0xffff0000, v211
	v_pk_add_f32 v[104:105], v[104:105], v[122:123]
	v_pk_add_f32 v[102:103], v[102:103], v[166:167]
	v_pk_add_f32 v[118:119], v[98:99], v[168:169]
	v_mul_f32_e32 v121, v111, v111
	v_mul_f32_e32 v122, v113, v113
	v_cvt_pk_bf16_f32 v98, v110, v111
	v_cvt_pk_bf16_f32 v99, v112, v113
	v_mul_f32_e32 v111, v107, v107
	v_mul_f32_e32 v113, v109, v109
	v_pk_add_f32 v[100:101], v[100:101], v[124:125]
	v_cvt_pk_bf16_f32 v120, v106, v107
	v_mul_f32_e32 v107, v103, v103
	v_mul_f32_e32 v123, v105, v105
	v_fmac_f32_e32 v121, v110, v110
	v_fmac_f32_e32 v122, v112, v112
	v_fmac_f32_e32 v111, v106, v106
	v_fmac_f32_e32 v113, v108, v108
	v_mul_f32_e32 v124, v119, v119
	v_mul_f32_e32 v125, v101, v101
	global_store_dwordx2 v[116:117], v[98:99], off
	v_fmac_f32_e32 v107, v102, v102
	v_fmac_f32_e32 v123, v104, v104
	v_add_f32_e32 v98, v121, v122
	v_add_f32_e32 v99, v111, v113
	v_fmac_f32_e32 v124, v118, v118
	v_fmac_f32_e32 v125, v100, v100
	v_add_f32_e32 v106, v107, v123
	v_add_f32_e32 v98, v98, v99
	v_add_f32_e32 v98, v98, v106
	v_add_f32_e32 v99, v124, v125
	v_add_f32_e32 v98, v98, v99
	ds_bpermute_b32 v99, v131, v98
	v_cvt_pk_bf16_f32 v102, v102, v103
	v_cvt_pk_bf16_f32 v103, v104, v105
	v_cvt_pk_bf16_f32 v121, v108, v109
	global_store_dwordx2 v[116:117], v[102:103], off offset:256
	s_waitcnt lgkmcnt(0)
	v_add_f32_e32 v98, v98, v99
	ds_bpermute_b32 v99, v135, v98
	v_cvt_pk_bf16_f32 v102, v118, v119
	v_cvt_pk_bf16_f32 v103, v100, v101
	global_store_dwordx2 v[116:117], v[120:121], off offset:32
	global_store_dwordx2 v[116:117], v[102:103], off offset:288
	s_and_saveexec_b64 s[30:31], s[8:9]
	s_cbranch_execz .LBB0_1687
	v_lshlrev_b64 v[100:101], 6, v[114:115]
	v_lshl_add_u64 v[100:101], s[16:17], 0, v[100:101]
	v_lshl_add_u64 v[100:101], s[28:29], 2, v[100:101]
	s_lshl_b32 s88, s45, 2
	v_lshl_add_u64 v[100:101], v[100:101], 0, s[88:89]
	s_waitcnt lgkmcnt(0)
	v_add_f32_e32 v98, v98, v99
	global_store_dword v[100:101], v98, off
.LBB0_1687:
	s_or_b64 exec, exec, s[30:31]
	v_add_u32_e32 v98, 32, v160
	s_waitcnt lgkmcnt(0)
	v_ashrrev_i32_e32 v99, 31, v98
	v_lshlrev_b64 v[100:101], 11, v[98:99]
	v_lshl_add_u64 v[100:101], s[14:15], 0, v[100:101]
	v_lshl_add_u64 v[100:101], v[158:159], 1, v[100:101]
	s_waitcnt vmcnt(28)
	v_lshlrev_b32_e32 v110, 16, v212
	v_and_b32_e32 v111, 0xffff0000, v212
	v_lshlrev_b32_e32 v102, 16, v213
	v_and_b32_e32 v103, 0xffff0000, v213
	v_lshlrev_b32_e32 v112, 16, v214
	v_and_b32_e32 v113, 0xffff0000, v214
	v_lshlrev_b32_e32 v104, 16, v215
	v_and_b32_e32 v105, 0xffff0000, v215
	v_lshlrev_b32_e32 v114, 16, v216
	v_and_b32_e32 v115, 0xffff0000, v216
	v_lshlrev_b32_e32 v106, 16, v217
	v_and_b32_e32 v107, 0xffff0000, v217
	v_lshlrev_b32_e32 v116, 16, v218
	v_and_b32_e32 v117, 0xffff0000, v218
	v_pk_add_f32 v[96:97], v[96:97], v[102:103]
	v_pk_add_f32 v[94:95], v[94:95], v[110:111]
	v_pk_add_f32 v[92:93], v[92:93], v[104:105]
	v_pk_add_f32 v[90:91], v[90:91], v[112:113]
	v_lshlrev_b32_e32 v108, 16, v219
	v_and_b32_e32 v109, 0xffff0000, v219
	v_pk_add_f32 v[88:89], v[88:89], v[106:107]
	v_pk_add_f32 v[86:87], v[86:87], v[114:115]
	v_pk_add_f32 v[102:103], v[82:83], v[116:117]
	v_mul_f32_e32 v105, v95, v95
	v_mul_f32_e32 v106, v97, v97
	v_cvt_pk_bf16_f32 v82, v94, v95
	v_cvt_pk_bf16_f32 v83, v96, v97
	v_mul_f32_e32 v95, v91, v91
	v_mul_f32_e32 v97, v93, v93
	v_pk_add_f32 v[84:85], v[84:85], v[108:109]
	v_cvt_pk_bf16_f32 v104, v90, v91
	v_mul_f32_e32 v91, v87, v87
	v_mul_f32_e32 v107, v89, v89
	v_fmac_f32_e32 v105, v94, v94
	v_fmac_f32_e32 v106, v96, v96
	v_fmac_f32_e32 v95, v90, v90
	v_fmac_f32_e32 v97, v92, v92
	v_mul_f32_e32 v108, v103, v103
	v_mul_f32_e32 v109, v85, v85
	global_store_dwordx2 v[100:101], v[82:83], off
	v_fmac_f32_e32 v91, v86, v86
	v_fmac_f32_e32 v107, v88, v88
	v_add_f32_e32 v82, v105, v106
	v_add_f32_e32 v83, v95, v97
	v_fmac_f32_e32 v108, v102, v102
	v_fmac_f32_e32 v109, v84, v84
	v_add_f32_e32 v90, v91, v107
	v_add_f32_e32 v82, v82, v83
	v_add_f32_e32 v82, v82, v90
	v_add_f32_e32 v83, v108, v109
	v_add_f32_e32 v82, v82, v83
	ds_bpermute_b32 v83, v131, v82
	v_cvt_pk_bf16_f32 v86, v86, v87
	v_cvt_pk_bf16_f32 v87, v88, v89
	v_cvt_pk_bf16_f32 v105, v92, v93
	global_store_dwordx2 v[100:101], v[86:87], off offset:256
	s_waitcnt lgkmcnt(0)
	v_add_f32_e32 v82, v82, v83
	ds_bpermute_b32 v83, v135, v82
	v_cvt_pk_bf16_f32 v86, v102, v103
	v_cvt_pk_bf16_f32 v87, v84, v85
	global_store_dwordx2 v[100:101], v[104:105], off offset:32
	global_store_dwordx2 v[100:101], v[86:87], off offset:288
	s_and_saveexec_b64 s[30:31], s[8:9]
	s_cbranch_execz .LBB0_1689
	v_lshlrev_b64 v[84:85], 6, v[98:99]
	v_lshl_add_u64 v[84:85], s[16:17], 0, v[84:85]
	v_lshl_add_u64 v[84:85], s[28:29], 2, v[84:85]
	s_lshl_b32 s88, s45, 2
	v_lshl_add_u64 v[84:85], v[84:85], 0, s[88:89]
	s_waitcnt lgkmcnt(0)
	v_add_f32_e32 v82, v82, v83
	global_store_dword v[84:85], v82, off
; __device__ __forceinline__ float bf_lo(unsigned u) { return __uint_as_float(u << 16); }
; __device__ __forceinline__ float bf_hi(unsigned u) { return __uint_as_float(u & 0xffff0000u); }
; __device__ __forceinline__ unsigned pk_bf16(float lo, float hi) { const f32x2 v = {lo, hi}; const bf16x2_t b = __builtin_convertvector(v, bf16x2_t); return __builtin_bit_cast(unsigned, b); }
;     __device__ __forceinline__ void operator()(const f32x4 (&acc)[2][2][4][2], const pg8::Unit& u, int wr, int wc, int fr, int fq) const {
;     ...
;         for (int ai = 0; ai < 2; ++ai)
; #pragma unroll
;             for (int m = 0; m < 4; ++m) {
;                 const int row = row0 + ai * 128 + m * 16; const size_t off = (size_t)row * DM + col0; float q = 0.f;
;                 f32x4 r4[2][2];
;                 if (rf32) {
; #pragma unroll
;                     for (int bj = 0; bj < 2; ++bj)
; #pragma unroll
;                         for (int n = 0; n < 2; ++n) r4[bj][n] = *(const f32x4*)(rp + off + bj * 128 + n * 16);
;                 } else {
; #pragma unroll
;                     for (int bj = 0; bj < 2; ++bj)
; #pragma unroll
;                         for (int n = 0; n < 2; ++n) { const u32x2 w = *(const u32x2*)(XB + off + bj * 128 + n * 16); r4[bj][n] = (f32x4){bf_lo(w.x), bf_hi(w.x), bf_lo(w.y), bf_hi(w.y)}; }
;                 }
; #pragma unroll
;                 for (int bj = 0; bj < 2; ++bj)
; #pragma unroll
;                     for (int n = 0; n < 2; ++n) { const f32x4 x4 = r4[bj][n] + acc[ai][bj][m][n];
;                         q += (x4[0] * x4[0] + x4[1] * x4[1]) + (x4[2] * x4[2] + x4[3] * x4[3]);
;                         u32x2 w; w.x = pk_bf16(x4[0], x4[1]); w.y = pk_bf16(x4[2], x4[3]); *(u32x2*)(XB + off + bj * 128 + n * 16) = w; }
;                 q += __shfl_xor(q, 16); q += __shfl_xor(q, 32);
;                 if (fq == 0) ssq[(size_t)row * 16 + u.pn * 4 + wc] = q;
.LBB0_1689:
	s_or_b64 exec, exec, s[30:31]
	v_add_u32_e32 v82, 48, v160
	s_waitcnt lgkmcnt(0)
	v_ashrrev_i32_e32 v83, 31, v82
	v_lshlrev_b64 v[84:85], 11, v[82:83]
	v_lshl_add_u64 v[84:85], s[14:15], 0, v[84:85]
	v_lshl_add_u64 v[84:85], v[158:159], 1, v[84:85]
	s_waitcnt vmcnt(28)
	v_lshlrev_b32_e32 v94, 16, v220
	v_and_b32_e32 v95, 0xffff0000, v220
	v_lshlrev_b32_e32 v86, 16, v221
	v_and_b32_e32 v87, 0xffff0000, v221
	v_lshlrev_b32_e32 v96, 16, v222
	v_and_b32_e32 v97, 0xffff0000, v222
	v_lshlrev_b32_e32 v88, 16, v223
	v_and_b32_e32 v89, 0xffff0000, v223
	v_lshlrev_b32_e32 v98, 16, v224
	v_and_b32_e32 v99, 0xffff0000, v224
	v_lshlrev_b32_e32 v90, 16, v225
	v_and_b32_e32 v91, 0xffff0000, v225
	v_lshlrev_b32_e32 v100, 16, v226
	v_and_b32_e32 v101, 0xffff0000, v226
	v_pk_add_f32 v[80:81], v[80:81], v[86:87]
	v_pk_add_f32 v[78:79], v[78:79], v[94:95]
	v_pk_add_f32 v[76:77], v[76:77], v[88:89]
	v_pk_add_f32 v[74:75], v[74:75], v[96:97]
	v_lshlrev_b32_e32 v92, 16, v227
	v_and_b32_e32 v93, 0xffff0000, v227
	v_pk_add_f32 v[72:73], v[72:73], v[90:91]
	v_pk_add_f32 v[70:71], v[70:71], v[98:99]
	v_pk_add_f32 v[86:87], v[66:67], v[100:101]
	v_mul_f32_e32 v89, v79, v79
	v_mul_f32_e32 v90, v81, v81
	v_cvt_pk_bf16_f32 v66, v78, v79
	v_cvt_pk_bf16_f32 v67, v80, v81
	v_mul_f32_e32 v79, v75, v75
	v_mul_f32_e32 v81, v77, v77
	v_pk_add_f32 v[68:69], v[68:69], v[92:93]
	v_cvt_pk_bf16_f32 v88, v74, v75
	v_mul_f32_e32 v75, v71, v71
	v_mul_f32_e32 v91, v73, v73
	v_fmac_f32_e32 v89, v78, v78
	v_fmac_f32_e32 v90, v80, v80
	v_fmac_f32_e32 v79, v74, v74
	v_fmac_f32_e32 v81, v76, v76
	v_mul_f32_e32 v92, v87, v87
	v_mul_f32_e32 v93, v69, v69
	global_store_dwordx2 v[84:85], v[66:67], off
	v_fmac_f32_e32 v75, v70, v70
	v_fmac_f32_e32 v91, v72, v72
	v_add_f32_e32 v66, v89, v90
	v_add_f32_e32 v67, v79, v81
	v_fmac_f32_e32 v92, v86, v86
	v_fmac_f32_e32 v93, v68, v68
	v_add_f32_e32 v74, v75, v91
	v_add_f32_e32 v66, v66, v67
	v_add_f32_e32 v66, v66, v74
	v_add_f32_e32 v67, v92, v93
	v_add_f32_e32 v66, v66, v67
	ds_bpermute_b32 v67, v131, v66
	v_cvt_pk_bf16_f32 v70, v70, v71
	v_cvt_pk_bf16_f32 v71, v72, v73
	v_cvt_pk_bf16_f32 v89, v76, v77
	global_store_dwordx2 v[84:85], v[70:71], off offset:256
	s_waitcnt lgkmcnt(0)
	v_add_f32_e32 v66, v66, v67
	ds_bpermute_b32 v67, v135, v66
	v_cvt_pk_bf16_f32 v70, v86, v87
	v_cvt_pk_bf16_f32 v71, v68, v69
	global_store_dwordx2 v[84:85], v[88:89], off offset:32
	global_store_dwordx2 v[84:85], v[70:71], off offset:288
	s_and_saveexec_b64 s[30:31], s[8:9]
	s_cbranch_execz .LBB0_1691
	v_lshlrev_b64 v[68:69], 6, v[82:83]
	v_lshl_add_u64 v[68:69], s[16:17], 0, v[68:69]
	v_lshl_add_u64 v[68:69], s[28:29], 2, v[68:69]
	s_lshl_b32 s88, s45, 2
	v_lshl_add_u64 v[68:69], v[68:69], 0, s[88:89]
	s_waitcnt lgkmcnt(0)
	v_add_f32_e32 v66, v66, v67
	global_store_dword v[68:69], v66, off
.LBB0_1691:
	s_or_b64 exec, exec, s[30:31]
	v_add_u32_e32 v66, 0x80, v160
	s_waitcnt lgkmcnt(0)
	v_ashrrev_i32_e32 v67, 31, v66
	v_lshlrev_b64 v[68:69], 11, v[66:67]
	v_lshl_add_u64 v[68:69], s[14:15], 0, v[68:69]
	v_lshl_add_u64 v[68:69], v[158:159], 1, v[68:69]
	s_waitcnt vmcnt(28)
	v_lshlrev_b32_e32 v78, 16, v228
	v_and_b32_e32 v79, 0xffff0000, v228
	v_lshlrev_b32_e32 v70, 16, v229
	v_and_b32_e32 v71, 0xffff0000, v229
	v_lshlrev_b32_e32 v80, 16, v230
	v_and_b32_e32 v81, 0xffff0000, v230
	v_lshlrev_b32_e32 v72, 16, v231
	v_and_b32_e32 v73, 0xffff0000, v231
	v_lshlrev_b32_e32 v82, 16, v232
	v_and_b32_e32 v83, 0xffff0000, v232
	v_lshlrev_b32_e32 v74, 16, v233
	v_and_b32_e32 v75, 0xffff0000, v233
	v_lshlrev_b32_e32 v84, 16, v234
	v_and_b32_e32 v85, 0xffff0000, v234
	v_pk_add_f32 v[64:65], v[64:65], v[70:71]
	v_pk_add_f32 v[62:63], v[62:63], v[78:79]
	v_pk_add_f32 v[60:61], v[60:61], v[72:73]
	v_pk_add_f32 v[58:59], v[58:59], v[80:81]
	v_lshlrev_b32_e32 v76, 16, v235
	v_and_b32_e32 v77, 0xffff0000, v235
	v_pk_add_f32 v[56:57], v[56:57], v[74:75]
	v_pk_add_f32 v[54:55], v[54:55], v[82:83]
	v_pk_add_f32 v[70:71], v[50:51], v[84:85]
	v_mul_f32_e32 v73, v63, v63
	v_mul_f32_e32 v74, v65, v65
	v_cvt_pk_bf16_f32 v50, v62, v63
	v_cvt_pk_bf16_f32 v51, v64, v65
	v_mul_f32_e32 v63, v59, v59
	v_mul_f32_e32 v65, v61, v61
	v_pk_add_f32 v[52:53], v[52:53], v[76:77]
	v_cvt_pk_bf16_f32 v72, v58, v59
	v_mul_f32_e32 v59, v55, v55
	v_mul_f32_e32 v75, v57, v57
	v_fmac_f32_e32 v73, v62, v62
	v_fmac_f32_e32 v74, v64, v64
	v_fmac_f32_e32 v63, v58, v58
	v_fmac_f32_e32 v65, v60, v60
	v_mul_f32_e32 v76, v71, v71
	v_mul_f32_e32 v77, v53, v53
	global_store_dwordx2 v[68:69], v[50:51], off
	v_fmac_f32_e32 v59, v54, v54
	v_fmac_f32_e32 v75, v56, v56
	v_add_f32_e32 v50, v73, v74
	v_add_f32_e32 v51, v63, v65
	v_fmac_f32_e32 v76, v70, v70
	v_fmac_f32_e32 v77, v52, v52
	v_add_f32_e32 v58, v59, v75
	v_add_f32_e32 v50, v50, v51
	v_add_f32_e32 v50, v50, v58
	v_add_f32_e32 v51, v76, v77
	v_add_f32_e32 v50, v50, v51
	ds_bpermute_b32 v51, v131, v50
	v_cvt_pk_bf16_f32 v54, v54, v55
	v_cvt_pk_bf16_f32 v55, v56, v57
	v_cvt_pk_bf16_f32 v73, v60, v61
	global_store_dwordx2 v[68:69], v[54:55], off offset:256
	s_waitcnt lgkmcnt(0)
	v_add_f32_e32 v50, v50, v51
	ds_bpermute_b32 v51, v135, v50
	v_cvt_pk_bf16_f32 v54, v70, v71
	v_cvt_pk_bf16_f32 v55, v52, v53
	global_store_dwordx2 v[68:69], v[72:73], off offset:32
	global_store_dwordx2 v[68:69], v[54:55], off offset:288
	s_and_saveexec_b64 s[30:31], s[8:9]
	s_cbranch_execz .LBB0_1693
	v_lshlrev_b64 v[52:53], 6, v[66:67]
	v_lshl_add_u64 v[52:53], s[16:17], 0, v[52:53]
	v_lshl_add_u64 v[52:53], s[28:29], 2, v[52:53]
	s_lshl_b32 s88, s45, 2
	v_lshl_add_u64 v[52:53], v[52:53], 0, s[88:89]
	s_waitcnt lgkmcnt(0)
	v_add_f32_e32 v50, v50, v51
	global_store_dword v[52:53], v50, off
; __device__ __forceinline__ float bf_lo(unsigned u) { return __uint_as_float(u << 16); }
; __device__ __forceinline__ float bf_hi(unsigned u) { return __uint_as_float(u & 0xffff0000u); }
; __device__ __forceinline__ unsigned pk_bf16(float lo, float hi) { const f32x2 v = {lo, hi}; const bf16x2_t b = __builtin_convertvector(v, bf16x2_t); return __builtin_bit_cast(unsigned, b); }
;     __device__ __forceinline__ void operator()(const f32x4 (&acc)[2][2][4][2], const pg8::Unit& u, int wr, int wc, int fr, int fq) const {
;     ...
;         for (int ai = 0; ai < 2; ++ai)
; #pragma unroll
;             for (int m = 0; m < 4; ++m) {
;                 const int row = row0 + ai * 128 + m * 16; const size_t off = (size_t)row * DM + col0; float q = 0.f;
;                 f32x4 r4[2][2];
;                 if (rf32) {
; #pragma unroll
;                     for (int bj = 0; bj < 2; ++bj)
; #pragma unroll
;                         for (int n = 0; n < 2; ++n) r4[bj][n] = *(const f32x4*)(rp + off + bj * 128 + n * 16);
;                 } else {
; #pragma unroll
;                     for (int bj = 0; bj < 2; ++bj)
; #pragma unroll
;                         for (int n = 0; n < 2; ++n) { const u32x2 w = *(const u32x2*)(XB + off + bj * 128 + n * 16); r4[bj][n] = (f32x4){bf_lo(w.x), bf_hi(w.x), bf_lo(w.y), bf_hi(w.y)}; }
;                 }
; #pragma unroll
;                 for (int bj = 0; bj < 2; ++bj)
; #pragma unroll
;                     for (int n = 0; n < 2; ++n) { const f32x4 x4 = r4[bj][n] + acc[ai][bj][m][n];
;                         q += (x4[0] * x4[0] + x4[1] * x4[1]) + (x4[2] * x4[2] + x4[3] * x4[3]);
;                         u32x2 w; w.x = pk_bf16(x4[0], x4[1]); w.y = pk_bf16(x4[2], x4[3]); *(u32x2*)(XB + off + bj * 128 + n * 16) = w; }
;                 q += __shfl_xor(q, 16); q += __shfl_xor(q, 32);
;                 if (fq == 0) ssq[(size_t)row * 16 + u.pn * 4 + wc] = q;
.LBB0_1693:
	s_or_b64 exec, exec, s[30:31]
	v_add_u32_e32 v50, 0x90, v160
	s_waitcnt lgkmcnt(0)
	v_ashrrev_i32_e32 v51, 31, v50
	v_lshlrev_b64 v[52:53], 11, v[50:51]
	v_lshl_add_u64 v[52:53], s[14:15], 0, v[52:53]
	v_lshl_add_u64 v[52:53], v[158:159], 1, v[52:53]
	s_waitcnt vmcnt(28)
	v_lshlrev_b32_e32 v62, 16, v236
	v_and_b32_e32 v63, 0xffff0000, v236
	v_lshlrev_b32_e32 v54, 16, v237
	v_and_b32_e32 v55, 0xffff0000, v237
	v_lshlrev_b32_e32 v64, 16, v238
	v_and_b32_e32 v65, 0xffff0000, v238
	v_lshlrev_b32_e32 v56, 16, v239
	v_and_b32_e32 v57, 0xffff0000, v239
	v_lshlrev_b32_e32 v66, 16, v240
	v_and_b32_e32 v67, 0xffff0000, v240
	v_lshlrev_b32_e32 v58, 16, v241
	v_and_b32_e32 v59, 0xffff0000, v241
	v_lshlrev_b32_e32 v68, 16, v242
	v_and_b32_e32 v69, 0xffff0000, v242
	v_pk_add_f32 v[48:49], v[48:49], v[54:55]
	v_pk_add_f32 v[46:47], v[46:47], v[62:63]
	v_pk_add_f32 v[44:45], v[44:45], v[56:57]
	v_pk_add_f32 v[42:43], v[42:43], v[64:65]
	v_lshlrev_b32_e32 v60, 16, v243
	v_and_b32_e32 v61, 0xffff0000, v243
	v_pk_add_f32 v[40:41], v[40:41], v[58:59]
	v_pk_add_f32 v[38:39], v[38:39], v[66:67]
	v_pk_add_f32 v[54:55], v[34:35], v[68:69]
	v_mul_f32_e32 v57, v47, v47
	v_mul_f32_e32 v58, v49, v49
	v_cvt_pk_bf16_f32 v34, v46, v47
	v_cvt_pk_bf16_f32 v35, v48, v49
	v_mul_f32_e32 v47, v43, v43
	v_mul_f32_e32 v49, v45, v45
	v_pk_add_f32 v[36:37], v[36:37], v[60:61]
	v_cvt_pk_bf16_f32 v56, v42, v43
	v_mul_f32_e32 v43, v39, v39
	v_mul_f32_e32 v59, v41, v41
	v_fmac_f32_e32 v57, v46, v46
	v_fmac_f32_e32 v58, v48, v48
	v_fmac_f32_e32 v47, v42, v42
	v_fmac_f32_e32 v49, v44, v44
	v_mul_f32_e32 v60, v55, v55
	v_mul_f32_e32 v61, v37, v37
	global_store_dwordx2 v[52:53], v[34:35], off
	v_fmac_f32_e32 v43, v38, v38
	v_fmac_f32_e32 v59, v40, v40
	v_add_f32_e32 v34, v57, v58
	v_add_f32_e32 v35, v47, v49
	v_fmac_f32_e32 v60, v54, v54
	v_fmac_f32_e32 v61, v36, v36
	v_add_f32_e32 v42, v43, v59
	v_add_f32_e32 v34, v34, v35
	v_add_f32_e32 v34, v34, v42
	v_add_f32_e32 v35, v60, v61
	v_add_f32_e32 v34, v34, v35
	ds_bpermute_b32 v35, v131, v34
	v_cvt_pk_bf16_f32 v38, v38, v39
	v_cvt_pk_bf16_f32 v39, v40, v41
	v_cvt_pk_bf16_f32 v57, v44, v45
	global_store_dwordx2 v[52:53], v[38:39], off offset:256
	s_waitcnt lgkmcnt(0)
	v_add_f32_e32 v34, v34, v35
	ds_bpermute_b32 v35, v135, v34
	v_cvt_pk_bf16_f32 v38, v54, v55
	v_cvt_pk_bf16_f32 v39, v36, v37
	global_store_dwordx2 v[52:53], v[56:57], off offset:32
	global_store_dwordx2 v[52:53], v[38:39], off offset:288
	s_and_saveexec_b64 s[30:31], s[8:9]
	s_cbranch_execz .LBB0_1695
	v_lshlrev_b64 v[36:37], 6, v[50:51]
	v_lshl_add_u64 v[36:37], s[16:17], 0, v[36:37]
	v_lshl_add_u64 v[36:37], s[28:29], 2, v[36:37]
	s_lshl_b32 s88, s45, 2
	v_lshl_add_u64 v[36:37], v[36:37], 0, s[88:89]
	s_waitcnt lgkmcnt(0)
	v_add_f32_e32 v34, v34, v35
	global_store_dword v[36:37], v34, off
; __device__ __forceinline__ float bf_lo(unsigned u) { return __uint_as_float(u << 16); }
; __device__ __forceinline__ float bf_hi(unsigned u) { return __uint_as_float(u & 0xffff0000u); }
; __device__ __forceinline__ unsigned pk_bf16(float lo, float hi) { const f32x2 v = {lo, hi}; const bf16x2_t b = __builtin_convertvector(v, bf16x2_t); return __builtin_bit_cast(unsigned, b); }
;     __device__ __forceinline__ void operator()(const f32x4 (&acc)[2][2][4][2], const pg8::Unit& u, int wr, int wc, int fr, int fq) const {
;     ...
;         for (int ai = 0; ai < 2; ++ai)
; #pragma unroll
;             for (int m = 0; m < 4; ++m) {
;                 const int row = row0 + ai * 128 + m * 16; const size_t off = (size_t)row * DM + col0; float q = 0.f;
;                 f32x4 r4[2][2];
;                 if (rf32) {
; #pragma unroll
;                     for (int bj = 0; bj < 2; ++bj)
; #pragma unroll
;                         for (int n = 0; n < 2; ++n) r4[bj][n] = *(const f32x4*)(rp + off + bj * 128 + n * 16);
;                 } else {
; #pragma unroll
;                     for (int bj = 0; bj < 2; ++bj)
; #pragma unroll
;                         for (int n = 0; n < 2; ++n) { const u32x2 w = *(const u32x2*)(XB + off + bj * 128 + n * 16); r4[bj][n] = (f32x4){bf_lo(w.x), bf_hi(w.x), bf_lo(w.y), bf_hi(w.y)}; }
;                 }
; #pragma unroll
;                 for (int bj = 0; bj < 2; ++bj)
; #pragma unroll
;                     for (int n = 0; n < 2; ++n) { const f32x4 x4 = r4[bj][n] + acc[ai][bj][m][n];
;                         q += (x4[0] * x4[0] + x4[1] * x4[1]) + (x4[2] * x4[2] + x4[3] * x4[3]);
;                         u32x2 w; w.x = pk_bf16(x4[0], x4[1]); w.y = pk_bf16(x4[2], x4[3]); *(u32x2*)(XB + off + bj * 128 + n * 16) = w; }
;                 q += __shfl_xor(q, 16); q += __shfl_xor(q, 32);
;                 if (fq == 0) ssq[(size_t)row * 16 + u.pn * 4 + wc] = q;
.LBB0_1695:
	s_or_b64 exec, exec, s[30:31]
	v_add_u32_e32 v34, 0xa0, v160
	s_waitcnt lgkmcnt(0)
	v_ashrrev_i32_e32 v35, 31, v34
	v_lshlrev_b64 v[36:37], 11, v[34:35]
	v_lshl_add_u64 v[36:37], s[14:15], 0, v[36:37]
	v_lshl_add_u64 v[36:37], v[158:159], 1, v[36:37]
	s_waitcnt vmcnt(28)
	v_lshlrev_b32_e32 v46, 16, v244
	v_and_b32_e32 v47, 0xffff0000, v244
	v_lshlrev_b32_e32 v38, 16, v245
	v_and_b32_e32 v39, 0xffff0000, v245
	v_lshlrev_b32_e32 v48, 16, v246
	v_and_b32_e32 v49, 0xffff0000, v246
	v_lshlrev_b32_e32 v40, 16, v247
	v_and_b32_e32 v41, 0xffff0000, v247
	v_lshlrev_b32_e32 v50, 16, v248
	v_and_b32_e32 v51, 0xffff0000, v248
	v_lshlrev_b32_e32 v42, 16, v249
	v_and_b32_e32 v43, 0xffff0000, v249
	v_lshlrev_b32_e32 v52, 16, v250
	v_and_b32_e32 v53, 0xffff0000, v250
	v_pk_add_f32 v[32:33], v[32:33], v[38:39]
	v_pk_add_f32 v[30:31], v[30:31], v[46:47]
	v_pk_add_f32 v[28:29], v[28:29], v[40:41]
	v_pk_add_f32 v[26:27], v[26:27], v[48:49]
	v_lshlrev_b32_e32 v44, 16, v251
	v_and_b32_e32 v45, 0xffff0000, v251
	v_pk_add_f32 v[24:25], v[24:25], v[42:43]
	v_pk_add_f32 v[22:23], v[22:23], v[50:51]
	v_pk_add_f32 v[38:39], v[18:19], v[52:53]
	v_mul_f32_e32 v41, v31, v31
	v_mul_f32_e32 v42, v33, v33
	v_cvt_pk_bf16_f32 v18, v30, v31
	v_cvt_pk_bf16_f32 v19, v32, v33
	v_mul_f32_e32 v31, v27, v27
	v_mul_f32_e32 v33, v29, v29
	v_pk_add_f32 v[20:21], v[20:21], v[44:45]
	v_cvt_pk_bf16_f32 v40, v26, v27
	v_mul_f32_e32 v27, v23, v23
	v_mul_f32_e32 v43, v25, v25
	v_fmac_f32_e32 v41, v30, v30
	v_fmac_f32_e32 v42, v32, v32
	v_fmac_f32_e32 v31, v26, v26
	v_fmac_f32_e32 v33, v28, v28
	v_mul_f32_e32 v44, v39, v39
	v_mul_f32_e32 v45, v21, v21
	global_store_dwordx2 v[36:37], v[18:19], off
	v_fmac_f32_e32 v27, v22, v22
	v_fmac_f32_e32 v43, v24, v24
	v_add_f32_e32 v18, v41, v42
	v_add_f32_e32 v19, v31, v33
	v_fmac_f32_e32 v44, v38, v38
	v_fmac_f32_e32 v45, v20, v20
	v_add_f32_e32 v26, v27, v43
	v_add_f32_e32 v18, v18, v19
	v_add_f32_e32 v18, v18, v26
	v_add_f32_e32 v19, v44, v45
	v_add_f32_e32 v18, v18, v19
	ds_bpermute_b32 v19, v131, v18
	v_cvt_pk_bf16_f32 v22, v22, v23
	v_cvt_pk_bf16_f32 v23, v24, v25
	v_cvt_pk_bf16_f32 v41, v28, v29
	global_store_dwordx2 v[36:37], v[22:23], off offset:256
	s_waitcnt lgkmcnt(0)
	v_add_f32_e32 v18, v18, v19
	ds_bpermute_b32 v19, v135, v18
	v_cvt_pk_bf16_f32 v22, v38, v39
	v_cvt_pk_bf16_f32 v23, v20, v21
	global_store_dwordx2 v[36:37], v[40:41], off offset:32
	global_store_dwordx2 v[36:37], v[22:23], off offset:288
	s_and_saveexec_b64 s[30:31], s[8:9]
	s_cbranch_execz .LBB0_1697
	v_lshlrev_b64 v[20:21], 6, v[34:35]
	v_lshl_add_u64 v[20:21], s[16:17], 0, v[20:21]
	v_lshl_add_u64 v[20:21], s[28:29], 2, v[20:21]
	s_lshl_b32 s88, s45, 2
	v_lshl_add_u64 v[20:21], v[20:21], 0, s[88:89]
	s_waitcnt lgkmcnt(0)
	v_add_f32_e32 v18, v18, v19
	global_store_dword v[20:21], v18, off
.LBB0_1697:
	s_or_b64 exec, exec, s[30:31]
	v_add_u32_e32 v18, 0xb0, v160
	s_waitcnt lgkmcnt(0)
	v_ashrrev_i32_e32 v19, 31, v18
	v_lshlrev_b64 v[20:21], 11, v[18:19]
	v_lshl_add_u64 v[20:21], s[14:15], 0, v[20:21]
	v_lshl_add_u64 v[20:21], v[158:159], 1, v[20:21]
	s_waitcnt vmcnt(28)
	v_lshlrev_b32_e32 v30, 16, v184
	v_and_b32_e32 v31, 0xffff0000, v184
	v_lshlrev_b32_e32 v22, 16, v185
	v_and_b32_e32 v23, 0xffff0000, v185
	v_lshlrev_b32_e32 v32, 16, v186
	v_and_b32_e32 v33, 0xffff0000, v186
	v_lshlrev_b32_e32 v24, 16, v187
	v_and_b32_e32 v25, 0xffff0000, v187
	v_lshlrev_b32_e32 v34, 16, v188
	v_and_b32_e32 v35, 0xffff0000, v188
	v_lshlrev_b32_e32 v26, 16, v189
	v_and_b32_e32 v27, 0xffff0000, v189
	v_lshlrev_b32_e32 v36, 16, v202
	v_and_b32_e32 v37, 0xffff0000, v202
	v_pk_add_f32 v[16:17], v[16:17], v[22:23]
	v_pk_add_f32 v[14:15], v[14:15], v[30:31]
	v_pk_add_f32 v[12:13], v[12:13], v[24:25]
	v_pk_add_f32 v[10:11], v[10:11], v[32:33]
	v_lshlrev_b32_e32 v28, 16, v203
	v_and_b32_e32 v29, 0xffff0000, v203
	v_pk_add_f32 v[8:9], v[8:9], v[26:27]
	v_pk_add_f32 v[6:7], v[6:7], v[34:35]
	v_pk_add_f32 v[22:23], v[2:3], v[36:37]
	v_mul_f32_e32 v25, v15, v15
	v_mul_f32_e32 v26, v17, v17
	v_cvt_pk_bf16_f32 v2, v14, v15
	v_cvt_pk_bf16_f32 v3, v16, v17
	v_mul_f32_e32 v15, v11, v11
	v_mul_f32_e32 v17, v13, v13
	v_pk_add_f32 v[4:5], v[4:5], v[28:29]
	v_cvt_pk_bf16_f32 v24, v10, v11
	v_mul_f32_e32 v11, v7, v7
	v_mul_f32_e32 v27, v9, v9
	v_fmac_f32_e32 v25, v14, v14
	v_fmac_f32_e32 v26, v16, v16
	v_fmac_f32_e32 v15, v10, v10
	v_fmac_f32_e32 v17, v12, v12
	v_mul_f32_e32 v28, v23, v23
	v_mul_f32_e32 v29, v5, v5
	global_store_dwordx2 v[20:21], v[2:3], off
	v_fmac_f32_e32 v11, v6, v6
	v_fmac_f32_e32 v27, v8, v8
	v_add_f32_e32 v2, v25, v26
	v_add_f32_e32 v3, v15, v17
	v_fmac_f32_e32 v28, v22, v22
	v_fmac_f32_e32 v29, v4, v4
	v_add_f32_e32 v10, v11, v27
	v_add_f32_e32 v2, v2, v3
	v_add_f32_e32 v2, v2, v10
	v_add_f32_e32 v3, v28, v29
	v_add_f32_e32 v2, v2, v3
	ds_bpermute_b32 v3, v131, v2
	v_cvt_pk_bf16_f32 v6, v6, v7
	v_cvt_pk_bf16_f32 v7, v8, v9
	v_cvt_pk_bf16_f32 v25, v12, v13
	global_store_dwordx2 v[20:21], v[6:7], off offset:256
	s_waitcnt lgkmcnt(0)
	v_add_f32_e32 v2, v2, v3
	ds_bpermute_b32 v3, v135, v2
	v_cvt_pk_bf16_f32 v6, v22, v23
	v_cvt_pk_bf16_f32 v7, v4, v5
	global_store_dwordx2 v[20:21], v[24:25], off offset:32
	global_store_dwordx2 v[20:21], v[6:7], off offset:288
	s_and_saveexec_b64 s[30:31], s[8:9]
	s_cbranch_execz .LBB0_1699
	v_lshlrev_b64 v[4:5], 6, v[18:19]
	v_lshl_add_u64 v[4:5], s[16:17], 0, v[4:5]
	v_lshl_add_u64 v[4:5], s[28:29], 2, v[4:5]
	s_lshl_b32 s88, s45, 2
	v_lshl_add_u64 v[4:5], v[4:5], 0, s[88:89]
	s_waitcnt lgkmcnt(0)
	v_add_f32_e32 v2, v2, v3
	global_store_dword v[4:5], v2, off

; __device__ __forceinline__ float bf_lo(unsigned u) { return __uint_as_float(u << 16); }
; __device__ __forceinline__ float bf_hi(unsigned u) { return __uint_as_float(u & 0xffff0000u); }
; __device__ __forceinline__ unsigned pk_bf16(float lo, float hi) { const f32x2 v = {lo, hi}; const bf16x2_t b = __builtin_convertvector(v, bf16x2_t); return __builtin_bit_cast(unsigned, b); }
;     __device__ __forceinline__ void operator()(const f32x4 (&acc)[2][2][4][2], const pg8::Unit& u, int wr, int wc, int fr, int fq) const {
;         asm volatile("" : "+v"(fr));
;         const int row0 = u.pm * 256 + wr * 64 + fr, col0 = u.pn * 256 + wc * 32 + 4 * fq;
;         const bool rf32 = (rp != nullptr) && (u.pm < MP / 256);
; #pragma unroll
;         for (int ai = 0; ai < 2; ++ai)
; #pragma unroll
;             for (int m = 0; m < 4; ++m) {
;                 const int row = row0 + ai * 128 + m * 16; const size_t off = (size_t)row * DM + col0; float q = 0.f;
;                 f32x4 r4[2][2];
;                 if (rf32) {
; #pragma unroll
;                     for (int bj = 0; bj < 2; ++bj)
; #pragma unroll
;                         for (int n = 0; n < 2; ++n) r4[bj][n] = *(const f32x4*)(rp + off + bj * 128 + n * 16);
;                 } else {
; #pragma unroll
;                     for (int bj = 0; bj < 2; ++bj)
; #pragma unroll
;                         for (int n = 0; n < 2; ++n) { const u32x2 w = *(const u32x2*)(XB + off + bj * 128 + n * 16); r4[bj][n] = (f32x4){bf_lo(w.x), bf_hi(w.x), bf_lo(w.y), bf_hi(w.y)}; }
;                 }
; #pragma unroll
;                 for (int bj = 0; bj < 2; ++bj)
; #pragma unroll
;                     for (int n = 0; n < 2; ++n) { const f32x4 x4 = r4[bj][n] + acc[ai][bj][m][n];
;                         q += (x4[0] * x4[0] + x4[1] * x4[1]) + (x4[2] * x4[2] + x4[3] * x4[3]);
;                         u32x2 w; w.x = pk_bf16(x4[0], x4[1]); w.y = pk_bf16(x4[2], x4[3]); *(u32x2*)(XB + off + bj * 128 + n * 16) = w; }
;                 q += __shfl_xor(q, 16); q += __shfl_xor(q, 32);
;                 if (fq == 0) ssq[(size_t)row * 16 + u.pn * 4 + wc] = q;
.LBB0_1893:
	s_lshl_b32 s4, s47, 8
	v_mov_b32_e32 v158, v1
	s_add_i32 s4, s4, s40
	s_lshl_b32 s22, s46, 2
	v_add_u32_e32 v160, s4, v158
	v_ashrrev_i32_e32 v161, 31, v160
	v_lshl_or_b32 v158, s46, 8, v163
	v_lshlrev_b64 v[166:167], 11, v[160:161]
	v_ashrrev_i32_e32 v159, 31, v158
	v_lshl_add_u64 v[166:167], s[14:15], 0, v[166:167]
	v_lshl_add_u64 v[166:167], v[158:159], 1, v[166:167]
	v_lshlrev_b32_e32 v252, 11, v160
	v_lshl_add_u32 v252, v158, 1, v252
	global_load_dwordx2 v[184:185], v252, s[14:15]
	global_load_dwordx2 v[186:187], v252, s[14:15] offset:32
	global_load_dwordx2 v[188:189], v252, s[14:15] offset:256
	global_load_dwordx2 v[202:203], v252, s[14:15] offset:288
	v_add_u32_e32 v253, 0x8000, v252
	global_load_dwordx2 v[204:205], v253, s[14:15]
	global_load_dwordx2 v[206:207], v253, s[14:15] offset:32
	global_load_dwordx2 v[208:209], v253, s[14:15] offset:256
	global_load_dwordx2 v[210:211], v253, s[14:15] offset:288
	v_add_u32_e32 v253, 0x10000, v252
	global_load_dwordx2 v[212:213], v253, s[14:15]
	global_load_dwordx2 v[214:215], v253, s[14:15] offset:32
	global_load_dwordx2 v[216:217], v253, s[14:15] offset:256
	global_load_dwordx2 v[218:219], v253, s[14:15] offset:288
	v_add_u32_e32 v253, 0x18000, v252
	global_load_dwordx2 v[220:221], v253, s[14:15]
	global_load_dwordx2 v[222:223], v253, s[14:15] offset:32
	global_load_dwordx2 v[224:225], v253, s[14:15] offset:256
	global_load_dwordx2 v[226:227], v253, s[14:15] offset:288
	v_add_u32_e32 v253, 0x40000, v252
	global_load_dwordx2 v[228:229], v253, s[14:15]
	global_load_dwordx2 v[230:231], v253, s[14:15] offset:32
	global_load_dwordx2 v[232:233], v253, s[14:15] offset:256
	global_load_dwordx2 v[234:235], v253, s[14:15] offset:288
	v_add_u32_e32 v253, 0x48000, v252
	global_load_dwordx2 v[236:237], v253, s[14:15]
	global_load_dwordx2 v[238:239], v253, s[14:15] offset:32
	global_load_dwordx2 v[240:241], v253, s[14:15] offset:256
	global_load_dwordx2 v[242:243], v253, s[14:15] offset:288
	v_add_u32_e32 v253, 0x50000, v252
	global_load_dwordx2 v[244:245], v253, s[14:15]
	global_load_dwordx2 v[246:247], v253, s[14:15] offset:32
	global_load_dwordx2 v[248:249], v253, s[14:15] offset:256
	global_load_dwordx2 v[250:251], v253, s[14:15] offset:288
	s_ashr_i32 s23, s22, 31
	s_waitcnt vmcnt(24)
	v_lshlrev_b32_e32 v176, 16, v184
	v_and_b32_e32 v177, 0xffff0000, v184
	v_lshlrev_b32_e32 v168, 16, v185
	v_and_b32_e32 v169, 0xffff0000, v185
	v_lshlrev_b32_e32 v178, 16, v186
	v_and_b32_e32 v179, 0xffff0000, v186
	v_lshlrev_b32_e32 v170, 16, v187
	v_and_b32_e32 v171, 0xffff0000, v187
	v_lshlrev_b32_e32 v180, 16, v188
	v_and_b32_e32 v181, 0xffff0000, v188
	v_lshlrev_b32_e32 v172, 16, v189
	v_and_b32_e32 v173, 0xffff0000, v189
	v_lshlrev_b32_e32 v182, 16, v202
	v_and_b32_e32 v183, 0xffff0000, v202
	v_pk_add_f32 v[128:129], v[128:129], v[168:169]
	v_pk_add_f32 v[126:127], v[126:127], v[176:177]
	v_pk_add_f32 v[124:125], v[124:125], v[170:171]
	v_pk_add_f32 v[122:123], v[122:123], v[178:179]
	v_lshlrev_b32_e32 v174, 16, v203
	v_and_b32_e32 v175, 0xffff0000, v203
	v_add_u32_e32 v253, 0x58000, v252
	global_load_dwordx2 v[184:185], v253, s[14:15]
	global_load_dwordx2 v[186:187], v253, s[14:15] offset:32
	global_load_dwordx2 v[188:189], v253, s[14:15] offset:256
	global_load_dwordx2 v[202:203], v253, s[14:15] offset:288
	v_pk_add_f32 v[120:121], v[120:121], v[172:173]
	v_pk_add_f32 v[118:119], v[118:119], v[180:181]
	v_pk_add_f32 v[168:169], v[114:115], v[182:183]
	v_mul_f32_e32 v165, v127, v127
	v_mul_f32_e32 v171, v129, v129
	v_cvt_pk_bf16_f32 v114, v126, v127
	v_cvt_pk_bf16_f32 v115, v128, v129
	v_mul_f32_e32 v127, v123, v123
	v_mul_f32_e32 v129, v125, v125
	v_pk_add_f32 v[116:117], v[116:117], v[174:175]
	v_cvt_pk_bf16_f32 v170, v122, v123
	v_mul_f32_e32 v123, v119, v119
	v_mul_f32_e32 v172, v121, v121
	v_fmac_f32_e32 v165, v126, v126
	v_fmac_f32_e32 v171, v128, v128
	v_fmac_f32_e32 v127, v122, v122
	v_fmac_f32_e32 v129, v124, v124
	v_mul_f32_e32 v173, v169, v169
	v_mul_f32_e32 v174, v117, v117
	global_store_dwordx2 v[166:167], v[114:115], off
	v_fmac_f32_e32 v123, v118, v118
	v_fmac_f32_e32 v172, v120, v120
	v_add_f32_e32 v114, v165, v171
	v_add_f32_e32 v115, v127, v129
	v_fmac_f32_e32 v173, v168, v168
	v_fmac_f32_e32 v174, v116, v116
	v_add_f32_e32 v122, v123, v172
	v_add_f32_e32 v114, v114, v115
	v_add_f32_e32 v114, v114, v122
	v_add_f32_e32 v115, v173, v174
	v_add_f32_e32 v114, v114, v115
	ds_bpermute_b32 v115, v131, v114
	v_cvt_pk_bf16_f32 v118, v118, v119
	v_cvt_pk_bf16_f32 v119, v120, v121
	v_cvt_pk_bf16_f32 v171, v124, v125
	global_store_dwordx2 v[166:167], v[118:119], off offset:256
	s_waitcnt lgkmcnt(0)
	v_add_f32_e32 v114, v114, v115
	ds_bpermute_b32 v115, v135, v114
	v_cvt_pk_bf16_f32 v118, v168, v169
	v_cvt_pk_bf16_f32 v119, v116, v117
	global_store_dwordx2 v[166:167], v[170:171], off offset:32
	global_store_dwordx2 v[166:167], v[118:119], off offset:288
	s_and_saveexec_b64 s[24:25], s[6:7]
	s_cbranch_execz .LBB0_1895
	v_lshlrev_b64 v[116:117], 6, v[160:161]
	v_lshl_add_u64 v[116:117], s[16:17], 0, v[116:117]
	v_lshl_add_u64 v[116:117], s[22:23], 2, v[116:117]
	s_lshl_b32 s88, s39, 2
	v_lshl_add_u64 v[116:117], v[116:117], 0, s[88:89]
	s_waitcnt lgkmcnt(0)
	v_add_f32_e32 v114, v114, v115
	global_store_dword v[116:117], v114, off
; __device__ __forceinline__ float bf_lo(unsigned u) { return __uint_as_float(u << 16); }
; __device__ __forceinline__ float bf_hi(unsigned u) { return __uint_as_float(u & 0xffff0000u); }
; __device__ __forceinline__ unsigned pk_bf16(float lo, float hi) { const f32x2 v = {lo, hi}; const bf16x2_t b = __builtin_convertvector(v, bf16x2_t); return __builtin_bit_cast(unsigned, b); }
;     __device__ __forceinline__ void operator()(const f32x4 (&acc)[2][2][4][2], const pg8::Unit& u, int wr, int wc, int fr, int fq) const {
;     ...
;         for (int ai = 0; ai < 2; ++ai)
; #pragma unroll
;             for (int m = 0; m < 4; ++m) {
;                 const int row = row0 + ai * 128 + m * 16; const size_t off = (size_t)row * DM + col0; float q = 0.f;
;                 f32x4 r4[2][2];
;                 if (rf32) {
; #pragma unroll
;                     for (int bj = 0; bj < 2; ++bj)
; #pragma unroll
;                         for (int n = 0; n < 2; ++n) r4[bj][n] = *(const f32x4*)(rp + off + bj * 128 + n * 16);
;                 } else {
; #pragma unroll
;                     for (int bj = 0; bj < 2; ++bj)
; #pragma unroll
;                         for (int n = 0; n < 2; ++n) { const u32x2 w = *(const u32x2*)(XB + off + bj * 128 + n * 16); r4[bj][n] = (f32x4){bf_lo(w.x), bf_hi(w.x), bf_lo(w.y), bf_hi(w.y)}; }
;                 }
; #pragma unroll
;                 for (int bj = 0; bj < 2; ++bj)
; #pragma unroll
;                     for (int n = 0; n < 2; ++n) { const f32x4 x4 = r4[bj][n] + acc[ai][bj][m][n];
;                         q += (x4[0] * x4[0] + x4[1] * x4[1]) + (x4[2] * x4[2] + x4[3] * x4[3]);
;                         u32x2 w; w.x = pk_bf16(x4[0], x4[1]); w.y = pk_bf16(x4[2], x4[3]); *(u32x2*)(XB + off + bj * 128 + n * 16) = w; }
;                 q += __shfl_xor(q, 16); q += __shfl_xor(q, 32);
;                 if (fq == 0) ssq[(size_t)row * 16 + u.pn * 4 + wc] = q;
.LBB0_1895:
	s_or_b64 exec, exec, s[24:25]
	v_add_u32_e32 v114, 16, v160
	s_waitcnt lgkmcnt(0)
	v_ashrrev_i32_e32 v115, 31, v114
	v_lshlrev_b64 v[116:117], 11, v[114:115]
	v_lshl_add_u64 v[116:117], s[14:15], 0, v[116:117]
	v_lshl_add_u64 v[116:117], v[158:159], 1, v[116:117]
	s_waitcnt vmcnt(28)
	v_lshlrev_b32_e32 v126, 16, v204
	v_and_b32_e32 v127, 0xffff0000, v204
	v_lshlrev_b32_e32 v118, 16, v205
	v_and_b32_e32 v119, 0xffff0000, v205
	v_lshlrev_b32_e32 v128, 16, v206
	v_and_b32_e32 v129, 0xffff0000, v206
	v_lshlrev_b32_e32 v120, 16, v207
	v_and_b32_e32 v121, 0xffff0000, v207
	v_lshlrev_b32_e32 v166, 16, v208
	v_and_b32_e32 v167, 0xffff0000, v208
	v_lshlrev_b32_e32 v122, 16, v209
	v_and_b32_e32 v123, 0xffff0000, v209
	v_lshlrev_b32_e32 v168, 16, v210
	v_and_b32_e32 v169, 0xffff0000, v210
	v_pk_add_f32 v[112:113], v[112:113], v[118:119]
	v_pk_add_f32 v[110:111], v[110:111], v[126:127]
	v_pk_add_f32 v[108:109], v[108:109], v[120:121]
	v_pk_add_f32 v[106:107], v[106:107], v[128:129]
	v_lshlrev_b32_e32 v124, 16, v211
	v_and_b32_e32 v125, 0xffff0000, v211
	v_pk_add_f32 v[104:105], v[104:105], v[122:123]
	v_pk_add_f32 v[102:103], v[102:103], v[166:167]
	v_pk_add_f32 v[118:119], v[98:99], v[168:169]
	v_mul_f32_e32 v121, v111, v111
	v_mul_f32_e32 v122, v113, v113
	v_cvt_pk_bf16_f32 v98, v110, v111
	v_cvt_pk_bf16_f32 v99, v112, v113
	v_mul_f32_e32 v111, v107, v107
	v_mul_f32_e32 v113, v109, v109
	v_pk_add_f32 v[100:101], v[100:101], v[124:125]
	v_cvt_pk_bf16_f32 v120, v106, v107
	v_mul_f32_e32 v107, v103, v103
	v_mul_f32_e32 v123, v105, v105
	v_fmac_f32_e32 v121, v110, v110
	v_fmac_f32_e32 v122, v112, v112
	v_fmac_f32_e32 v111, v106, v106
	v_fmac_f32_e32 v113, v108, v108
	v_mul_f32_e32 v124, v119, v119
	v_mul_f32_e32 v125, v101, v101
	global_store_dwordx2 v[116:117], v[98:99], off
	v_fmac_f32_e32 v107, v102, v102
	v_fmac_f32_e32 v123, v104, v104
	v_add_f32_e32 v98, v121, v122
	v_add_f32_e32 v99, v111, v113
	v_fmac_f32_e32 v124, v118, v118
	v_fmac_f32_e32 v125, v100, v100
	v_add_f32_e32 v106, v107, v123
	v_add_f32_e32 v98, v98, v99
	v_add_f32_e32 v98, v98, v106
	v_add_f32_e32 v99, v124, v125
	v_add_f32_e32 v98, v98, v99
	ds_bpermute_b32 v99, v131, v98
	v_cvt_pk_bf16_f32 v102, v102, v103
	v_cvt_pk_bf16_f32 v103, v104, v105
	v_cvt_pk_bf16_f32 v121, v108, v109
	global_store_dwordx2 v[116:117], v[102:103], off offset:256
	s_waitcnt lgkmcnt(0)
	v_add_f32_e32 v98, v98, v99
	ds_bpermute_b32 v99, v135, v98
	v_cvt_pk_bf16_f32 v102, v118, v119
	v_cvt_pk_bf16_f32 v103, v100, v101
	global_store_dwordx2 v[116:117], v[120:121], off offset:32
	global_store_dwordx2 v[116:117], v[102:103], off offset:288
	s_and_saveexec_b64 s[24:25], s[6:7]
	s_cbranch_execz .LBB0_1897
	v_lshlrev_b64 v[100:101], 6, v[114:115]
	v_lshl_add_u64 v[100:101], s[16:17], 0, v[100:101]
	v_lshl_add_u64 v[100:101], s[22:23], 2, v[100:101]
	s_lshl_b32 s88, s39, 2
	v_lshl_add_u64 v[100:101], v[100:101], 0, s[88:89]
	s_waitcnt lgkmcnt(0)
	v_add_f32_e32 v98, v98, v99
	global_store_dword v[100:101], v98, off
.LBB0_1897:
	s_or_b64 exec, exec, s[24:25]
	v_add_u32_e32 v98, 32, v160
	s_waitcnt lgkmcnt(0)
	v_ashrrev_i32_e32 v99, 31, v98
	v_lshlrev_b64 v[100:101], 11, v[98:99]
	v_lshl_add_u64 v[100:101], s[14:15], 0, v[100:101]
	v_lshl_add_u64 v[100:101], v[158:159], 1, v[100:101]
	s_waitcnt vmcnt(28)
	v_lshlrev_b32_e32 v110, 16, v212
	v_and_b32_e32 v111, 0xffff0000, v212
	v_lshlrev_b32_e32 v102, 16, v213
	v_and_b32_e32 v103, 0xffff0000, v213
	v_lshlrev_b32_e32 v112, 16, v214
	v_and_b32_e32 v113, 0xffff0000, v214
	v_lshlrev_b32_e32 v104, 16, v215
	v_and_b32_e32 v105, 0xffff0000, v215
	v_lshlrev_b32_e32 v114, 16, v216
	v_and_b32_e32 v115, 0xffff0000, v216
	v_lshlrev_b32_e32 v106, 16, v217
	v_and_b32_e32 v107, 0xffff0000, v217
	v_lshlrev_b32_e32 v116, 16, v218
	v_and_b32_e32 v117, 0xffff0000, v218
	v_pk_add_f32 v[96:97], v[96:97], v[102:103]
	v_pk_add_f32 v[94:95], v[94:95], v[110:111]
	v_pk_add_f32 v[92:93], v[92:93], v[104:105]
	v_pk_add_f32 v[90:91], v[90:91], v[112:113]
	v_lshlrev_b32_e32 v108, 16, v219
	v_and_b32_e32 v109, 0xffff0000, v219
	v_pk_add_f32 v[88:89], v[88:89], v[106:107]
	v_pk_add_f32 v[86:87], v[86:87], v[114:115]
	v_pk_add_f32 v[102:103], v[82:83], v[116:117]
	v_mul_f32_e32 v105, v95, v95
	v_mul_f32_e32 v106, v97, v97
	v_cvt_pk_bf16_f32 v82, v94, v95
	v_cvt_pk_bf16_f32 v83, v96, v97
	v_mul_f32_e32 v95, v91, v91
	v_mul_f32_e32 v97, v93, v93
	v_pk_add_f32 v[84:85], v[84:85], v[108:109]
	v_cvt_pk_bf16_f32 v104, v90, v91
	v_mul_f32_e32 v91, v87, v87
	v_mul_f32_e32 v107, v89, v89
	v_fmac_f32_e32 v105, v94, v94
	v_fmac_f32_e32 v106, v96, v96
	v_fmac_f32_e32 v95, v90, v90
	v_fmac_f32_e32 v97, v92, v92
	v_mul_f32_e32 v108, v103, v103
	v_mul_f32_e32 v109, v85, v85
	global_store_dwordx2 v[100:101], v[82:83], off
	v_fmac_f32_e32 v91, v86, v86
	v_fmac_f32_e32 v107, v88, v88
	v_add_f32_e32 v82, v105, v106
	v_add_f32_e32 v83, v95, v97
	v_fmac_f32_e32 v108, v102, v102
	v_fmac_f32_e32 v109, v84, v84
	v_add_f32_e32 v90, v91, v107
	v_add_f32_e32 v82, v82, v83
	v_add_f32_e32 v82, v82, v90
	v_add_f32_e32 v83, v108, v109
	v_add_f32_e32 v82, v82, v83
	ds_bpermute_b32 v83, v131, v82
	v_cvt_pk_bf16_f32 v86, v86, v87
	v_cvt_pk_bf16_f32 v87, v88, v89
	v_cvt_pk_bf16_f32 v105, v92, v93
	global_store_dwordx2 v[100:101], v[86:87], off offset:256
	s_waitcnt lgkmcnt(0)
	v_add_f32_e32 v82, v82, v83
	ds_bpermute_b32 v83, v135, v82
	v_cvt_pk_bf16_f32 v86, v102, v103
	v_cvt_pk_bf16_f32 v87, v84, v85
	global_store_dwordx2 v[100:101], v[104:105], off offset:32
	global_store_dwordx2 v[100:101], v[86:87], off offset:288
	s_and_saveexec_b64 s[24:25], s[6:7]
	s_cbranch_execz .LBB0_1899
	v_lshlrev_b64 v[84:85], 6, v[98:99]
	v_lshl_add_u64 v[84:85], s[16:17], 0, v[84:85]
	v_lshl_add_u64 v[84:85], s[22:23], 2, v[84:85]
	s_lshl_b32 s88, s39, 2
	v_lshl_add_u64 v[84:85], v[84:85], 0, s[88:89]
	s_waitcnt lgkmcnt(0)
	v_add_f32_e32 v82, v82, v83
	global_store_dword v[84:85], v82, off
; __device__ __forceinline__ float bf_lo(unsigned u) { return __uint_as_float(u << 16); }
; __device__ __forceinline__ float bf_hi(unsigned u) { return __uint_as_float(u & 0xffff0000u); }
; __device__ __forceinline__ unsigned pk_bf16(float lo, float hi) { const f32x2 v = {lo, hi}; const bf16x2_t b = __builtin_convertvector(v, bf16x2_t); return __builtin_bit_cast(unsigned, b); }
;     __device__ __forceinline__ void operator()(const f32x4 (&acc)[2][2][4][2], const pg8::Unit& u, int wr, int wc, int fr, int fq) const {
;     ...
;         for (int ai = 0; ai < 2; ++ai)
; #pragma unroll
;             for (int m = 0; m < 4; ++m) {
;                 const int row = row0 + ai * 128 + m * 16; const size_t off = (size_t)row * DM + col0; float q = 0.f;
;                 f32x4 r4[2][2];
;                 if (rf32) {
; #pragma unroll
;                     for (int bj = 0; bj < 2; ++bj)
; #pragma unroll
;                         for (int n = 0; n < 2; ++n) r4[bj][n] = *(const f32x4*)(rp + off + bj * 128 + n * 16);
;                 } else {
; #pragma unroll
;                     for (int bj = 0; bj < 2; ++bj)
; #pragma unroll
;                         for (int n = 0; n < 2; ++n) { const u32x2 w = *(const u32x2*)(XB + off + bj * 128 + n * 16); r4[bj][n] = (f32x4){bf_lo(w.x), bf_hi(w.x), bf_lo(w.y), bf_hi(w.y)}; }
;                 }
; #pragma unroll
;                 for (int bj = 0; bj < 2; ++bj)
; #pragma unroll
;                     for (int n = 0; n < 2; ++n) { const f32x4 x4 = r4[bj][n] + acc[ai][bj][m][n];
;                         q += (x4[0] * x4[0] + x4[1] * x4[1]) + (x4[2] * x4[2] + x4[3] * x4[3]);
;                         u32x2 w; w.x = pk_bf16(x4[0], x4[1]); w.y = pk_bf16(x4[2], x4[3]); *(u32x2*)(XB + off + bj * 128 + n * 16) = w; }
;                 q += __shfl_xor(q, 16); q += __shfl_xor(q, 32);
;                 if (fq == 0) ssq[(size_t)row * 16 + u.pn * 4 + wc] = q;
.LBB0_1899:
	s_or_b64 exec, exec, s[24:25]
	v_add_u32_e32 v82, 48, v160
	s_waitcnt lgkmcnt(0)
	v_ashrrev_i32_e32 v83, 31, v82
	v_lshlrev_b64 v[84:85], 11, v[82:83]
	v_lshl_add_u64 v[84:85], s[14:15], 0, v[84:85]
	v_lshl_add_u64 v[84:85], v[158:159], 1, v[84:85]
	s_waitcnt vmcnt(28)
	v_lshlrev_b32_e32 v94, 16, v220
	v_and_b32_e32 v95, 0xffff0000, v220
	v_lshlrev_b32_e32 v86, 16, v221
	v_and_b32_e32 v87, 0xffff0000, v221
	v_lshlrev_b32_e32 v96, 16, v222
	v_and_b32_e32 v97, 0xffff0000, v222
	v_lshlrev_b32_e32 v88, 16, v223
	v_and_b32_e32 v89, 0xffff0000, v223
	v_lshlrev_b32_e32 v98, 16, v224
	v_and_b32_e32 v99, 0xffff0000, v224
	v_lshlrev_b32_e32 v90, 16, v225
	v_and_b32_e32 v91, 0xffff0000, v225
	v_lshlrev_b32_e32 v100, 16, v226
	v_and_b32_e32 v101, 0xffff0000, v226
	v_pk_add_f32 v[80:81], v[80:81], v[86:87]
	v_pk_add_f32 v[78:79], v[78:79], v[94:95]
	v_pk_add_f32 v[76:77], v[76:77], v[88:89]
	v_pk_add_f32 v[74:75], v[74:75], v[96:97]
	v_lshlrev_b32_e32 v92, 16, v227
	v_and_b32_e32 v93, 0xffff0000, v227
	v_pk_add_f32 v[72:73], v[72:73], v[90:91]
	v_pk_add_f32 v[70:71], v[70:71], v[98:99]
	v_pk_add_f32 v[86:87], v[66:67], v[100:101]
	v_mul_f32_e32 v89, v79, v79
	v_mul_f32_e32 v90, v81, v81
	v_cvt_pk_bf16_f32 v66, v78, v79
	v_cvt_pk_bf16_f32 v67, v80, v81
	v_mul_f32_e32 v79, v75, v75
	v_mul_f32_e32 v81, v77, v77
	v_pk_add_f32 v[68:69], v[68:69], v[92:93]
	v_cvt_pk_bf16_f32 v88, v74, v75
	v_mul_f32_e32 v75, v71, v71
	v_mul_f32_e32 v91, v73, v73
	v_fmac_f32_e32 v89, v78, v78
	v_fmac_f32_e32 v90, v80, v80
	v_fmac_f32_e32 v79, v74, v74
	v_fmac_f32_e32 v81, v76, v76
	v_mul_f32_e32 v92, v87, v87
	v_mul_f32_e32 v93, v69, v69
	global_store_dwordx2 v[84:85], v[66:67], off
	v_fmac_f32_e32 v75, v70, v70
	v_fmac_f32_e32 v91, v72, v72
	v_add_f32_e32 v66, v89, v90
	v_add_f32_e32 v67, v79, v81
	v_fmac_f32_e32 v92, v86, v86
	v_fmac_f32_e32 v93, v68, v68
	v_add_f32_e32 v74, v75, v91
	v_add_f32_e32 v66, v66, v67
	v_add_f32_e32 v66, v66, v74
	v_add_f32_e32 v67, v92, v93
	v_add_f32_e32 v66, v66, v67
	ds_bpermute_b32 v67, v131, v66
	v_cvt_pk_bf16_f32 v70, v70, v71
	v_cvt_pk_bf16_f32 v71, v72, v73
	v_cvt_pk_bf16_f32 v89, v76, v77
	global_store_dwordx2 v[84:85], v[70:71], off offset:256
	s_waitcnt lgkmcnt(0)
	v_add_f32_e32 v66, v66, v67
	ds_bpermute_b32 v67, v135, v66
	v_cvt_pk_bf16_f32 v70, v86, v87
	v_cvt_pk_bf16_f32 v71, v68, v69
	global_store_dwordx2 v[84:85], v[88:89], off offset:32
	global_store_dwordx2 v[84:85], v[70:71], off offset:288
	s_and_saveexec_b64 s[24:25], s[6:7]
	s_cbranch_execz .LBB0_1901
	v_lshlrev_b64 v[68:69], 6, v[82:83]
	v_lshl_add_u64 v[68:69], s[16:17], 0, v[68:69]
	v_lshl_add_u64 v[68:69], s[22:23], 2, v[68:69]
	s_lshl_b32 s88, s39, 2
	v_lshl_add_u64 v[68:69], v[68:69], 0, s[88:89]
	s_waitcnt lgkmcnt(0)
	v_add_f32_e32 v66, v66, v67
	global_store_dword v[68:69], v66, off
.LBB0_1901:
	s_or_b64 exec, exec, s[24:25]
	v_add_u32_e32 v66, 0x80, v160
	s_waitcnt lgkmcnt(0)
	v_ashrrev_i32_e32 v67, 31, v66
	v_lshlrev_b64 v[68:69], 11, v[66:67]
	v_lshl_add_u64 v[68:69], s[14:15], 0, v[68:69]
	v_lshl_add_u64 v[68:69], v[158:159], 1, v[68:69]
	s_waitcnt vmcnt(28)
	v_lshlrev_b32_e32 v78, 16, v228
	v_and_b32_e32 v79, 0xffff0000, v228
	v_lshlrev_b32_e32 v70, 16, v229
	v_and_b32_e32 v71, 0xffff0000, v229
	v_lshlrev_b32_e32 v80, 16, v230
	v_and_b32_e32 v81, 0xffff0000, v230
	v_lshlrev_b32_e32 v72, 16, v231
	v_and_b32_e32 v73, 0xffff0000, v231
	v_lshlrev_b32_e32 v82, 16, v232
	v_and_b32_e32 v83, 0xffff0000, v232
	v_lshlrev_b32_e32 v74, 16, v233
	v_and_b32_e32 v75, 0xffff0000, v233
	v_lshlrev_b32_e32 v84, 16, v234
	v_and_b32_e32 v85, 0xffff0000, v234
	v_pk_add_f32 v[64:65], v[64:65], v[70:71]
	v_pk_add_f32 v[62:63], v[62:63], v[78:79]
	v_pk_add_f32 v[60:61], v[60:61], v[72:73]
	v_pk_add_f32 v[58:59], v[58:59], v[80:81]
	v_lshlrev_b32_e32 v76, 16, v235
	v_and_b32_e32 v77, 0xffff0000, v235
	v_pk_add_f32 v[56:57], v[56:57], v[74:75]
	v_pk_add_f32 v[54:55], v[54:55], v[82:83]
	v_pk_add_f32 v[70:71], v[50:51], v[84:85]
	v_mul_f32_e32 v73, v63, v63
	v_mul_f32_e32 v74, v65, v65
	v_cvt_pk_bf16_f32 v50, v62, v63
	v_cvt_pk_bf16_f32 v51, v64, v65
	v_mul_f32_e32 v63, v59, v59
	v_mul_f32_e32 v65, v61, v61
	v_pk_add_f32 v[52:53], v[52:53], v[76:77]
	v_cvt_pk_bf16_f32 v72, v58, v59
	v_mul_f32_e32 v59, v55, v55
	v_mul_f32_e32 v75, v57, v57
	v_fmac_f32_e32 v73, v62, v62
	v_fmac_f32_e32 v74, v64, v64
	v_fmac_f32_e32 v63, v58, v58
	v_fmac_f32_e32 v65, v60, v60
	v_mul_f32_e32 v76, v71, v71
	v_mul_f32_e32 v77, v53, v53
	global_store_dwordx2 v[68:69], v[50:51], off
	v_fmac_f32_e32 v59, v54, v54
	v_fmac_f32_e32 v75, v56, v56
	v_add_f32_e32 v50, v73, v74
	v_add_f32_e32 v51, v63, v65
	v_fmac_f32_e32 v76, v70, v70
	v_fmac_f32_e32 v77, v52, v52
	v_add_f32_e32 v58, v59, v75
	v_add_f32_e32 v50, v50, v51
	v_add_f32_e32 v50, v50, v58
	v_add_f32_e32 v51, v76, v77
	v_add_f32_e32 v50, v50, v51
	ds_bpermute_b32 v51, v131, v50
	v_cvt_pk_bf16_f32 v54, v54, v55
	v_cvt_pk_bf16_f32 v55, v56, v57
	v_cvt_pk_bf16_f32 v73, v60, v61
	global_store_dwordx2 v[68:69], v[54:55], off offset:256
	s_waitcnt lgkmcnt(0)
	v_add_f32_e32 v50, v50, v51
	ds_bpermute_b32 v51, v135, v50
	v_cvt_pk_bf16_f32 v54, v70, v71
	v_cvt_pk_bf16_f32 v55, v52, v53
	global_store_dwordx2 v[68:69], v[72:73], off offset:32
	global_store_dwordx2 v[68:69], v[54:55], off offset:288
	s_and_saveexec_b64 s[24:25], s[6:7]
	s_cbranch_execz .LBB0_1903
	v_lshlrev_b64 v[52:53], 6, v[66:67]
	v_lshl_add_u64 v[52:53], s[16:17], 0, v[52:53]
	v_lshl_add_u64 v[52:53], s[22:23], 2, v[52:53]
	s_lshl_b32 s88, s39, 2
	v_lshl_add_u64 v[52:53], v[52:53], 0, s[88:89]
	s_waitcnt lgkmcnt(0)
	v_add_f32_e32 v50, v50, v51
	global_store_dword v[52:53], v50, off
; __device__ __forceinline__ float bf_lo(unsigned u) { return __uint_as_float(u << 16); }
; __device__ __forceinline__ float bf_hi(unsigned u) { return __uint_as_float(u & 0xffff0000u); }
; __device__ __forceinline__ unsigned pk_bf16(float lo, float hi) { const f32x2 v = {lo, hi}; const bf16x2_t b = __builtin_convertvector(v, bf16x2_t); return __builtin_bit_cast(unsigned, b); }
;     __device__ __forceinline__ void operator()(const f32x4 (&acc)[2][2][4][2], const pg8::Unit& u, int wr, int wc, int fr, int fq) const {
;     ...
;         for (int ai = 0; ai < 2; ++ai)
; #pragma unroll
;             for (int m = 0; m < 4; ++m) {
;                 const int row = row0 + ai * 128 + m * 16; const size_t off = (size_t)row * DM + col0; float q = 0.f;
;                 f32x4 r4[2][2];
;                 if (rf32) {
; #pragma unroll
;                     for (int bj = 0; bj < 2; ++bj)
; #pragma unroll
;                         for (int n = 0; n < 2; ++n) r4[bj][n] = *(const f32x4*)(rp + off + bj * 128 + n * 16);
;                 } else {
; #pragma unroll
;                     for (int bj = 0; bj < 2; ++bj)
; #pragma unroll
;                         for (int n = 0; n < 2; ++n) { const u32x2 w = *(const u32x2*)(XB + off + bj * 128 + n * 16); r4[bj][n] = (f32x4){bf_lo(w.x), bf_hi(w.x), bf_lo(w.y), bf_hi(w.y)}; }
;                 }
; #pragma unroll
;                 for (int bj = 0; bj < 2; ++bj)
; #pragma unroll
;                     for (int n = 0; n < 2; ++n) { const f32x4 x4 = r4[bj][n] + acc[ai][bj][m][n];
;                         q += (x4[0] * x4[0] + x4[1] * x4[1]) + (x4[2] * x4[2] + x4[3] * x4[3]);
;                         u32x2 w; w.x = pk_bf16(x4[0], x4[1]); w.y = pk_bf16(x4[2], x4[3]); *(u32x2*)(XB + off + bj * 128 + n * 16) = w; }
;                 q += __shfl_xor(q, 16); q += __shfl_xor(q, 32);
;                 if (fq == 0) ssq[(size_t)row * 16 + u.pn * 4 + wc] = q;
.LBB0_1903:
	s_or_b64 exec, exec, s[24:25]
	v_add_u32_e32 v50, 0x90, v160
	s_waitcnt lgkmcnt(0)
	v_ashrrev_i32_e32 v51, 31, v50
	v_lshlrev_b64 v[52:53], 11, v[50:51]
	v_lshl_add_u64 v[52:53], s[14:15], 0, v[52:53]
	v_lshl_add_u64 v[52:53], v[158:159], 1, v[52:53]
	s_waitcnt vmcnt(28)
	v_lshlrev_b32_e32 v62, 16, v236
	v_and_b32_e32 v63, 0xffff0000, v236
	v_lshlrev_b32_e32 v54, 16, v237
	v_and_b32_e32 v55, 0xffff0000, v237
	v_lshlrev_b32_e32 v64, 16, v238
	v_and_b32_e32 v65, 0xffff0000, v238
	v_lshlrev_b32_e32 v56, 16, v239
	v_and_b32_e32 v57, 0xffff0000, v239
	v_lshlrev_b32_e32 v66, 16, v240
	v_and_b32_e32 v67, 0xffff0000, v240
	v_lshlrev_b32_e32 v58, 16, v241
	v_and_b32_e32 v59, 0xffff0000, v241
	v_lshlrev_b32_e32 v68, 16, v242
	v_and_b32_e32 v69, 0xffff0000, v242
	v_pk_add_f32 v[48:49], v[48:49], v[54:55]
	v_pk_add_f32 v[46:47], v[46:47], v[62:63]
	v_pk_add_f32 v[44:45], v[44:45], v[56:57]
	v_pk_add_f32 v[42:43], v[42:43], v[64:65]
	v_lshlrev_b32_e32 v60, 16, v243
	v_and_b32_e32 v61, 0xffff0000, v243
	v_pk_add_f32 v[40:41], v[40:41], v[58:59]
	v_pk_add_f32 v[38:39], v[38:39], v[66:67]
	v_pk_add_f32 v[54:55], v[34:35], v[68:69]
	v_mul_f32_e32 v57, v47, v47
	v_mul_f32_e32 v58, v49, v49
	v_cvt_pk_bf16_f32 v34, v46, v47
	v_cvt_pk_bf16_f32 v35, v48, v49
	v_mul_f32_e32 v47, v43, v43
	v_mul_f32_e32 v49, v45, v45
	v_pk_add_f32 v[36:37], v[36:37], v[60:61]
	v_cvt_pk_bf16_f32 v56, v42, v43
	v_mul_f32_e32 v43, v39, v39
	v_mul_f32_e32 v59, v41, v41
	v_fmac_f32_e32 v57, v46, v46
	v_fmac_f32_e32 v58, v48, v48
	v_fmac_f32_e32 v47, v42, v42
	v_fmac_f32_e32 v49, v44, v44
	v_mul_f32_e32 v60, v55, v55
	v_mul_f32_e32 v61, v37, v37
	global_store_dwordx2 v[52:53], v[34:35], off
	v_fmac_f32_e32 v43, v38, v38
	v_fmac_f32_e32 v59, v40, v40
	v_add_f32_e32 v34, v57, v58
	v_add_f32_e32 v35, v47, v49
	v_fmac_f32_e32 v60, v54, v54
	v_fmac_f32_e32 v61, v36, v36
	v_add_f32_e32 v42, v43, v59
	v_add_f32_e32 v34, v34, v35
	v_add_f32_e32 v34, v34, v42
	v_add_f32_e32 v35, v60, v61
	v_add_f32_e32 v34, v34, v35
	ds_bpermute_b32 v35, v131, v34
	v_cvt_pk_bf16_f32 v38, v38, v39
	v_cvt_pk_bf16_f32 v39, v40, v41
	v_cvt_pk_bf16_f32 v57, v44, v45
	global_store_dwordx2 v[52:53], v[38:39], off offset:256
	s_waitcnt lgkmcnt(0)
	v_add_f32_e32 v34, v34, v35
	ds_bpermute_b32 v35, v135, v34
	v_cvt_pk_bf16_f32 v38, v54, v55
	v_cvt_pk_bf16_f32 v39, v36, v37
	global_store_dwordx2 v[52:53], v[56:57], off offset:32
	global_store_dwordx2 v[52:53], v[38:39], off offset:288
	s_and_saveexec_b64 s[24:25], s[6:7]
	s_cbranch_execz .LBB0_1905
	v_lshlrev_b64 v[36:37], 6, v[50:51]
	v_lshl_add_u64 v[36:37], s[16:17], 0, v[36:37]
	v_lshl_add_u64 v[36:37], s[22:23], 2, v[36:37]
	s_lshl_b32 s88, s39, 2
	v_lshl_add_u64 v[36:37], v[36:37], 0, s[88:89]
	s_waitcnt lgkmcnt(0)
	v_add_f32_e32 v34, v34, v35
	global_store_dword v[36:37], v34, off
; __device__ __forceinline__ float bf_lo(unsigned u) { return __uint_as_float(u << 16); }
; __device__ __forceinline__ float bf_hi(unsigned u) { return __uint_as_float(u & 0xffff0000u); }
; __device__ __forceinline__ unsigned pk_bf16(float lo, float hi) { const f32x2 v = {lo, hi}; const bf16x2_t b = __builtin_convertvector(v, bf16x2_t); return __builtin_bit_cast(unsigned, b); }
;     __device__ __forceinline__ void operator()(const f32x4 (&acc)[2][2][4][2], const pg8::Unit& u, int wr, int wc, int fr, int fq) const {
;     ...
;         for (int ai = 0; ai < 2; ++ai)
; #pragma unroll
;             for (int m = 0; m < 4; ++m) {
;                 const int row = row0 + ai * 128 + m * 16; const size_t off = (size_t)row * DM + col0; float q = 0.f;
;                 f32x4 r4[2][2];
;                 if (rf32) {
; #pragma unroll
;                     for (int bj = 0; bj < 2; ++bj)
; #pragma unroll
;                         for (int n = 0; n < 2; ++n) r4[bj][n] = *(const f32x4*)(rp + off + bj * 128 + n * 16);
;                 } else {
; #pragma unroll
;                     for (int bj = 0; bj < 2; ++bj)
; #pragma unroll
;                         for (int n = 0; n < 2; ++n) { const u32x2 w = *(const u32x2*)(XB + off + bj * 128 + n * 16); r4[bj][n] = (f32x4){bf_lo(w.x), bf_hi(w.x), bf_lo(w.y), bf_hi(w.y)}; }
;                 }
; #pragma unroll
;                 for (int bj = 0; bj < 2; ++bj)
; #pragma unroll
;                     for (int n = 0; n < 2; ++n) { const f32x4 x4 = r4[bj][n] + acc[ai][bj][m][n];
;                         q += (x4[0] * x4[0] + x4[1] * x4[1]) + (x4[2] * x4[2] + x4[3] * x4[3]);
;                         u32x2 w; w.x = pk_bf16(x4[0], x4[1]); w.y = pk_bf16(x4[2], x4[3]); *(u32x2*)(XB + off + bj * 128 + n * 16) = w; }
;                 q += __shfl_xor(q, 16); q += __shfl_xor(q, 32);
;                 if (fq == 0) ssq[(size_t)row * 16 + u.pn * 4 + wc] = q;
.LBB0_1905:
	s_or_b64 exec, exec, s[24:25]
	v_add_u32_e32 v34, 0xa0, v160
	s_waitcnt lgkmcnt(0)
	v_ashrrev_i32_e32 v35, 31, v34
	v_lshlrev_b64 v[36:37], 11, v[34:35]
	v_lshl_add_u64 v[36:37], s[14:15], 0, v[36:37]
	v_lshl_add_u64 v[36:37], v[158:159], 1, v[36:37]
	s_waitcnt vmcnt(28)
	v_lshlrev_b32_e32 v46, 16, v244
	v_and_b32_e32 v47, 0xffff0000, v244
	v_lshlrev_b32_e32 v38, 16, v245
	v_and_b32_e32 v39, 0xffff0000, v245
	v_lshlrev_b32_e32 v48, 16, v246
	v_and_b32_e32 v49, 0xffff0000, v246
	v_lshlrev_b32_e32 v40, 16, v247
	v_and_b32_e32 v41, 0xffff0000, v247
	v_lshlrev_b32_e32 v50, 16, v248
	v_and_b32_e32 v51, 0xffff0000, v248
	v_lshlrev_b32_e32 v42, 16, v249
	v_and_b32_e32 v43, 0xffff0000, v249
	v_lshlrev_b32_e32 v52, 16, v250
	v_and_b32_e32 v53, 0xffff0000, v250
	v_pk_add_f32 v[32:33], v[32:33], v[38:39]
	v_pk_add_f32 v[30:31], v[30:31], v[46:47]
	v_pk_add_f32 v[28:29], v[28:29], v[40:41]
	v_pk_add_f32 v[26:27], v[26:27], v[48:49]
	v_lshlrev_b32_e32 v44, 16, v251
	v_and_b32_e32 v45, 0xffff0000, v251
	v_pk_add_f32 v[24:25], v[24:25], v[42:43]
	v_pk_add_f32 v[22:23], v[22:23], v[50:51]
	v_pk_add_f32 v[38:39], v[18:19], v[52:53]
	v_mul_f32_e32 v41, v31, v31
	v_mul_f32_e32 v42, v33, v33
	v_cvt_pk_bf16_f32 v18, v30, v31
	v_cvt_pk_bf16_f32 v19, v32, v33
	v_mul_f32_e32 v31, v27, v27
	v_mul_f32_e32 v33, v29, v29
	v_pk_add_f32 v[20:21], v[20:21], v[44:45]
	v_cvt_pk_bf16_f32 v40, v26, v27
	v_mul_f32_e32 v27, v23, v23
	v_mul_f32_e32 v43, v25, v25
	v_fmac_f32_e32 v41, v30, v30
	v_fmac_f32_e32 v42, v32, v32
	v_fmac_f32_e32 v31, v26, v26
	v_fmac_f32_e32 v33, v28, v28
	v_mul_f32_e32 v44, v39, v39
	v_mul_f32_e32 v45, v21, v21
	global_store_dwordx2 v[36:37], v[18:19], off
	v_fmac_f32_e32 v27, v22, v22
	v_fmac_f32_e32 v43, v24, v24
	v_add_f32_e32 v18, v41, v42
	v_add_f32_e32 v19, v31, v33
	v_fmac_f32_e32 v44, v38, v38
	v_fmac_f32_e32 v45, v20, v20
	v_add_f32_e32 v26, v27, v43
	v_add_f32_e32 v18, v18, v19
	v_add_f32_e32 v18, v18, v26
	v_add_f32_e32 v19, v44, v45
	v_add_f32_e32 v18, v18, v19
	ds_bpermute_b32 v19, v131, v18
	v_cvt_pk_bf16_f32 v22, v22, v23
	v_cvt_pk_bf16_f32 v23, v24, v25
	v_cvt_pk_bf16_f32 v41, v28, v29
	global_store_dwordx2 v[36:37], v[22:23], off offset:256
	s_waitcnt lgkmcnt(0)
	v_add_f32_e32 v18, v18, v19
	ds_bpermute_b32 v19, v135, v18
	v_cvt_pk_bf16_f32 v22, v38, v39
	v_cvt_pk_bf16_f32 v23, v20, v21
	global_store_dwordx2 v[36:37], v[40:41], off offset:32
	global_store_dwordx2 v[36:37], v[22:23], off offset:288
	s_and_saveexec_b64 s[24:25], s[6:7]
	s_cbranch_execz .LBB0_1907
	v_lshlrev_b64 v[20:21], 6, v[34:35]
	v_lshl_add_u64 v[20:21], s[16:17], 0, v[20:21]
	v_lshl_add_u64 v[20:21], s[22:23], 2, v[20:21]
	s_lshl_b32 s88, s39, 2
	v_lshl_add_u64 v[20:21], v[20:21], 0, s[88:89]
	s_waitcnt lgkmcnt(0)
	v_add_f32_e32 v18, v18, v19
	global_store_dword v[20:21], v18, off
.LBB0_1907:
	s_or_b64 exec, exec, s[24:25]
	v_add_u32_e32 v18, 0xb0, v160
	s_waitcnt lgkmcnt(0)
	v_ashrrev_i32_e32 v19, 31, v18
	v_lshlrev_b64 v[20:21], 11, v[18:19]
	v_lshl_add_u64 v[20:21], s[14:15], 0, v[20:21]
	v_lshl_add_u64 v[20:21], v[158:159], 1, v[20:21]
	s_waitcnt vmcnt(28)
	v_lshlrev_b32_e32 v30, 16, v184
	v_and_b32_e32 v31, 0xffff0000, v184
	v_lshlrev_b32_e32 v22, 16, v185
	v_and_b32_e32 v23, 0xffff0000, v185
	v_lshlrev_b32_e32 v32, 16, v186
	v_and_b32_e32 v33, 0xffff0000, v186
	v_lshlrev_b32_e32 v24, 16, v187
	v_and_b32_e32 v25, 0xffff0000, v187
	v_lshlrev_b32_e32 v34, 16, v188
	v_and_b32_e32 v35, 0xffff0000, v188
	v_lshlrev_b32_e32 v26, 16, v189
	v_and_b32_e32 v27, 0xffff0000, v189
	v_lshlrev_b32_e32 v36, 16, v202
	v_and_b32_e32 v37, 0xffff0000, v202
	v_pk_add_f32 v[16:17], v[16:17], v[22:23]
	v_pk_add_f32 v[14:15], v[14:15], v[30:31]
	v_pk_add_f32 v[12:13], v[12:13], v[24:25]
	v_pk_add_f32 v[10:11], v[10:11], v[32:33]
	v_lshlrev_b32_e32 v28, 16, v203
	v_and_b32_e32 v29, 0xffff0000, v203
	v_pk_add_f32 v[8:9], v[8:9], v[26:27]
	v_pk_add_f32 v[6:7], v[6:7], v[34:35]
	v_pk_add_f32 v[22:23], v[2:3], v[36:37]
	v_mul_f32_e32 v25, v15, v15
	v_mul_f32_e32 v26, v17, v17
	v_cvt_pk_bf16_f32 v2, v14, v15
	v_cvt_pk_bf16_f32 v3, v16, v17
	v_mul_f32_e32 v15, v11, v11
	v_mul_f32_e32 v17, v13, v13
	v_pk_add_f32 v[4:5], v[4:5], v[28:29]
	v_cvt_pk_bf16_f32 v24, v10, v11
	v_mul_f32_e32 v11, v7, v7
	v_mul_f32_e32 v27, v9, v9
	v_fmac_f32_e32 v25, v14, v14
	v_fmac_f32_e32 v26, v16, v16
	v_fmac_f32_e32 v15, v10, v10
	v_fmac_f32_e32 v17, v12, v12
	v_mul_f32_e32 v28, v23, v23
	v_mul_f32_e32 v29, v5, v5
	global_store_dwordx2 v[20:21], v[2:3], off
	v_fmac_f32_e32 v11, v6, v6
	v_fmac_f32_e32 v27, v8, v8
	v_add_f32_e32 v2, v25, v26
	v_add_f32_e32 v3, v15, v17
	v_fmac_f32_e32 v28, v22, v22
	v_fmac_f32_e32 v29, v4, v4
	v_add_f32_e32 v10, v11, v27
	v_add_f32_e32 v2, v2, v3
	v_add_f32_e32 v2, v2, v10
	v_add_f32_e32 v3, v28, v29
	v_add_f32_e32 v2, v2, v3
	ds_bpermute_b32 v3, v131, v2
	v_cvt_pk_bf16_f32 v6, v6, v7
	v_cvt_pk_bf16_f32 v7, v8, v9
	v_cvt_pk_bf16_f32 v25, v12, v13
	global_store_dwordx2 v[20:21], v[6:7], off offset:256
	s_waitcnt lgkmcnt(0)
	v_add_f32_e32 v2, v2, v3
	ds_bpermute_b32 v3, v135, v2
	v_cvt_pk_bf16_f32 v6, v22, v23
	v_cvt_pk_bf16_f32 v7, v4, v5
	global_store_dwordx2 v[20:21], v[24:25], off offset:32
	global_store_dwordx2 v[20:21], v[6:7], off offset:288
	s_and_saveexec_b64 s[24:25], s[6:7]
	s_cbranch_execz .LBB0_1909
	v_lshlrev_b64 v[4:5], 6, v[18:19]
	v_lshl_add_u64 v[4:5], s[16:17], 0, v[4:5]
	v_lshl_add_u64 v[4:5], s[22:23], 2, v[4:5]
	s_lshl_b32 s88, s39, 2
	v_lshl_add_u64 v[4:5], v[4:5], 0, s[88:89]
	s_waitcnt lgkmcnt(0)
	v_add_f32_e32 v2, v2, v3
	global_store_dword v[4:5], v2, off
